# GEMM K loops: the remaining 8 per-iteration 64-bit VALU address adds for LDS-DMA loads replaced by saddr-form loads (second-half bases computed on the scalar unit)
# speedup vs baseline: 1.0103x; 1.0021x over previous
; #define PG8_STAGE(bufoff, gbase, voff) do { _Pragma("unroll") for (int _i = 0; _i < 2; ++_i) \
;         __builtin_amdgcn_global_load_lds((const unsigned*)((const char*)(gbase) + (voff)[_i]), (PG8_LAS unsigned*)(lds + (bufoff) + ldsw + _i * 8192), 16, 0, 0); } while (0)
; #define PG8_LDA(dst, b, h) do { _Pragma("unroll") for (int m = 0; m < 4; ++m) _Pragma("unroll") for (int k = 0; k < 2; ++k) dst[m][k] = *(const PG8_LAS bf16x8*)(lds + PG8_SA(b, h) + aoff + m * 2048 + k * 1024); } while (0)
; #define PG8_LDB(dst, b, h) do { _Pragma("unroll") for (int n = 0; n < 2; ++n) _Pragma("unroll") for (int k = 0; k < 2; ++k) dst[n][k] = *(const PG8_LAS bf16x8*)(lds + PG8_SB(b, h) + boff + n * 2048 + k * 1024); } while (0)
; #define PG8_MMA(ai, bj, At, Bt) do { __builtin_amdgcn_s_setprio(1); _Pragma("unroll") for (int m = 0; m < 4; ++m) _Pragma("unroll") for (int n = 0; n < 2; ++n) _Pragma("unroll") for (int k = 0; k < 2; ++k) \
;         acc[ai][bj][m][n] = __builtin_amdgcn_mfma_f32_16x16x32_bf16(Bt[n][k], At[m][k], acc[ai][bj][m][n], 0, 0, 0); __builtin_amdgcn_s_setprio(0); } while (0)
; #define PG8_WAIT_V(n) asm volatile("s_waitcnt vmcnt(" #n ")" ::: "memory")
; #define PG8_WAIT_L(n) asm volatile("s_waitcnt lgkmcnt(" #n ")" ::: "memory")
; #define PG8_BAR __builtin_amdgcn_s_barrier()
; #define PG8_SCHED __builtin_amdgcn_sched_barrier(0)
; template <class Epi, class Sched, bool ALIGN_EPI = false, bool SP2 = false>
; __device__ __forceinline__ void gemm_phase(PG8_LAS unsigned char* lds, const Gemm g, const Sched& S, const Epi& E) {
;     ...
;             PG8_LDB(B0, 0, 0); PG8_LDB(B1, 0, 1); PG8_SCHED; PG8_LDA(At, 0, 0); PG8_STAGE(PG8_SA(1, 1), a1 + hstep, voffA);
;             PG8_WAIT_V(8); PG8_WAIT_L(0); PG8_BAR; PG8_MMA(0, 0, At, B0); PG8_MMA(0, 1, At, B1); PG8_BAR; PG8_SCHED;
;             PG8_LDA(At, 0, 1); PG8_STAGE(PG8_SB(0, 0), b2, voffB); PG8_STAGE(PG8_SB(0, 1), b2 + hstep, voffB); PG8_STAGE(PG8_SA(0, 0), a2, voffA);
;             PG8_WAIT_V(8); PG8_WAIT_L(0); PG8_BAR; PG8_MMA(1, 0, At, B0); PG8_MMA(1, 1, At, B1); PG8_BAR; PG8_SCHED;
.LBB0_120:
	ds_read_b128 v[152:155], v141
	ds_read_b128 v[164:167], v141 offset:1024
	ds_read_b128 v[168:171], v141 offset:2048
	ds_read_b128 v[172:175], v141 offset:3072
	ds_read_b128 v[176:179], v156
	ds_read_b128 v[180:183], v156 offset:1024
	ds_read_b128 v[184:187], v156 offset:2048
	ds_read_b128 v[188:191], v156 offset:3072
	s_add_u32 s36, s84, 0xfff80080
	s_addc_u32 s37, s85, -1
	s_cmp_eq_u32 s97, 28
	s_cselect_b32 s89, s28, s37
	s_cselect_b32 s88, s29, s36
	s_cselect_b32 s87, s73, s83
	s_cselect_b32 s86, s75, s81
	s_add_i32 m0, s9, 0xc000
	ds_read_b128 v[192:195], v157
	ds_read_b128 v[196:199], v157 offset:1024
	ds_read_b128 v[200:203], v157 offset:2048
	ds_read_b128 v[208:211], v157 offset:3072
	ds_read_b128 v[212:215], v157 offset:4096
	ds_read_b128 v[216:219], v157 offset:5120
	ds_read_b128 v[220:223], v157 offset:6144
	ds_read_b128 v[224:227], v157 offset:7168
	global_load_lds_dwordx4 v144, s[84:85]
	s_add_i32 m0, s9, 0xe000
	s_nop 0
	global_load_lds_dwordx4 v146, s[84:85]
	s_waitcnt vmcnt(8)
	s_waitcnt lgkmcnt(0)
	s_barrier
	s_setprio 1
	s_waitcnt lgkmcnt(0)
	v_mfma_f32_16x16x32_bf16 v[126:129], v[152:155], v[192:195], v[126:129]
	v_mfma_f32_16x16x32_bf16 v[122:125], v[168:171], v[192:195], v[122:125]
	v_mfma_f32_16x16x32_bf16 v[110:113], v[152:155], v[200:203], v[110:113]
	v_mfma_f32_16x16x32_bf16 v[106:109], v[168:171], v[200:203], v[106:109]
	v_mfma_f32_16x16x32_bf16 v[94:97], v[152:155], v[212:215], v[94:97]
	v_mfma_f32_16x16x32_bf16 v[90:93], v[168:171], v[212:215], v[90:93]
	v_mfma_f32_16x16x32_bf16 v[78:81], v[152:155], v[220:223], v[78:81]
	v_mfma_f32_16x16x32_bf16 v[74:77], v[168:171], v[220:223], v[74:77]
	v_mfma_f32_16x16x32_bf16 v[126:129], v[164:167], v[196:199], v[126:129]
	v_mfma_f32_16x16x32_bf16 v[122:125], v[172:175], v[196:199], v[122:125]
	v_mfma_f32_16x16x32_bf16 v[110:113], v[164:167], v[208:211], v[110:113]
	v_mfma_f32_16x16x32_bf16 v[106:109], v[172:175], v[208:211], v[106:109]
	v_mfma_f32_16x16x32_bf16 v[94:97], v[164:167], v[216:219], v[94:97]
	v_mfma_f32_16x16x32_bf16 v[90:93], v[172:175], v[216:219], v[90:93]
	v_mfma_f32_16x16x32_bf16 v[78:81], v[164:167], v[224:227], v[78:81]
	v_mfma_f32_16x16x32_bf16 v[74:77], v[172:175], v[224:227], v[74:77]
	s_setprio 0
	s_setprio 1
	v_mfma_f32_16x16x32_bf16 v[118:121], v[176:179], v[192:195], v[118:121]
	v_mfma_f32_16x16x32_bf16 v[114:117], v[184:187], v[192:195], v[114:117]
	v_mfma_f32_16x16x32_bf16 v[102:105], v[176:179], v[200:203], v[102:105]
	v_mfma_f32_16x16x32_bf16 v[98:101], v[184:187], v[200:203], v[98:101]
	v_mfma_f32_16x16x32_bf16 v[86:89], v[176:179], v[212:215], v[86:89]
	v_mfma_f32_16x16x32_bf16 v[82:85], v[184:187], v[212:215], v[82:85]
	v_mfma_f32_16x16x32_bf16 v[70:73], v[176:179], v[220:223], v[70:73]
	v_mfma_f32_16x16x32_bf16 v[66:69], v[184:187], v[220:223], v[66:69]
	v_mfma_f32_16x16x32_bf16 v[118:121], v[180:183], v[196:199], v[118:121]
	v_mfma_f32_16x16x32_bf16 v[114:117], v[188:191], v[196:199], v[114:117]
	v_mfma_f32_16x16x32_bf16 v[102:105], v[180:183], v[208:211], v[102:105]
	v_mfma_f32_16x16x32_bf16 v[98:101], v[188:191], v[208:211], v[98:101]
	v_mfma_f32_16x16x32_bf16 v[86:89], v[180:183], v[216:219], v[86:89]
	v_mfma_f32_16x16x32_bf16 v[82:85], v[188:191], v[216:219], v[82:85]
	v_mfma_f32_16x16x32_bf16 v[70:73], v[180:183], v[224:227], v[70:73]
	v_mfma_f32_16x16x32_bf16 v[66:69], v[188:191], v[224:227], v[66:69]
	s_setprio 0
	s_barrier
	s_add_u32 s98, s86, s22
	s_addc_u32 s99, s87, s23
	s_add_u32 s100, s88, s22
	s_addc_u32 s101, s89, s23
	s_add_i32 s36, s58, s8
	s_nop 0
	s_mov_b32 m0, s36
	ds_read_b128 v[192:195], v157 offset:16384
	ds_read_b128 v[196:199], v157 offset:17408
	ds_read_b128 v[200:203], v157 offset:18432
	ds_read_b128 v[208:211], v157 offset:19456
	ds_read_b128 v[212:215], v157 offset:20480
	ds_read_b128 v[216:219], v157 offset:21504
	ds_read_b128 v[220:223], v157 offset:22528
	ds_read_b128 v[224:227], v157 offset:23552
	global_load_lds_dwordx4 v132, s[86:87]
	s_add_i32 m0, s36, 0x2000
	s_add_u32 s36, s86, 0x80000
	s_nop 0
	s_addc_u32 s37, s87, 0
	s_add_i32 s40, s59, s8
	global_load_lds_dwordx4 v136, s[86:87]
	s_mov_b32 m0, s40
	s_nop 0
	global_load_lds_dwordx4 v132, s[36:37]
	s_add_i32 m0, s40, 0x2000
	s_nop 0
	global_load_lds_dwordx4 v136, s[36:37]
	s_nop 0
	s_mov_b32 m0, s9
	s_nop 0
	global_load_lds_dwordx4 v130, s[88:89]
	s_mov_b32 m0, s12
	s_nop 0
	global_load_lds_dwordx4 v134, s[88:89]
	s_waitcnt vmcnt(8)
	s_waitcnt lgkmcnt(0)
	s_barrier
	s_setprio 1
	s_waitcnt lgkmcnt(0)
	v_mfma_f32_16x16x32_bf16 v[62:65], v[152:155], v[192:195], v[62:65]
	v_mfma_f32_16x16x32_bf16 v[58:61], v[168:171], v[192:195], v[58:61]
	v_mfma_f32_16x16x32_bf16 v[46:49], v[152:155], v[200:203], v[46:49]
	v_mfma_f32_16x16x32_bf16 v[42:45], v[168:171], v[200:203], v[42:45]
	v_mfma_f32_16x16x32_bf16 v[30:33], v[152:155], v[212:215], v[30:33]
	v_mfma_f32_16x16x32_bf16 v[26:29], v[168:171], v[212:215], v[26:29]
	v_mfma_f32_16x16x32_bf16 v[14:17], v[152:155], v[220:223], v[14:17]
	v_mfma_f32_16x16x32_bf16 v[10:13], v[168:171], v[220:223], v[10:13]
	v_mfma_f32_16x16x32_bf16 v[62:65], v[164:167], v[196:199], v[62:65]
	v_mfma_f32_16x16x32_bf16 v[58:61], v[172:175], v[196:199], v[58:61]
	v_mfma_f32_16x16x32_bf16 v[46:49], v[164:167], v[208:211], v[46:49]
	v_mfma_f32_16x16x32_bf16 v[42:45], v[172:175], v[208:211], v[42:45]
	v_mfma_f32_16x16x32_bf16 v[30:33], v[164:167], v[216:219], v[30:33]
	v_mfma_f32_16x16x32_bf16 v[26:29], v[172:175], v[216:219], v[26:29]
	v_mfma_f32_16x16x32_bf16 v[14:17], v[164:167], v[224:227], v[14:17]
	v_mfma_f32_16x16x32_bf16 v[10:13], v[172:175], v[224:227], v[10:13]
	s_setprio 0
	s_setprio 1
	v_mfma_f32_16x16x32_bf16 v[54:57], v[176:179], v[192:195], v[54:57]
	v_mfma_f32_16x16x32_bf16 v[50:53], v[184:187], v[192:195], v[50:53]
	v_mfma_f32_16x16x32_bf16 v[38:41], v[176:179], v[200:203], v[38:41]
	v_mfma_f32_16x16x32_bf16 v[34:37], v[184:187], v[200:203], v[34:37]
	v_mfma_f32_16x16x32_bf16 v[22:25], v[176:179], v[212:215], v[22:25]
	v_mfma_f32_16x16x32_bf16 v[18:21], v[184:187], v[212:215], v[18:21]
	v_mfma_f32_16x16x32_bf16 v[6:9], v[176:179], v[220:223], v[6:9]
	v_mfma_f32_16x16x32_bf16 v[2:5], v[184:187], v[220:223], v[2:5]
	v_mfma_f32_16x16x32_bf16 v[54:57], v[180:183], v[196:199], v[54:57]
	v_mfma_f32_16x16x32_bf16 v[50:53], v[188:191], v[196:199], v[50:53]
	v_mfma_f32_16x16x32_bf16 v[38:41], v[180:183], v[208:211], v[38:41]
	v_mfma_f32_16x16x32_bf16 v[34:37], v[188:191], v[208:211], v[34:37]
	v_mfma_f32_16x16x32_bf16 v[22:25], v[180:183], v[216:219], v[22:25]
	v_mfma_f32_16x16x32_bf16 v[18:21], v[188:191], v[216:219], v[18:21]
	v_mfma_f32_16x16x32_bf16 v[6:9], v[180:183], v[224:227], v[6:9]
	v_mfma_f32_16x16x32_bf16 v[2:5], v[188:191], v[224:227], v[2:5]
	s_setprio 0
	s_barrier
; #define PG8_STAGE(bufoff, gbase, voff) do { _Pragma("unroll") for (int _i = 0; _i < 2; ++_i) \
;         __builtin_amdgcn_global_load_lds((const unsigned*)((const char*)(gbase) + (voff)[_i]), (PG8_LAS unsigned*)(lds + (bufoff) + ldsw + _i * 8192), 16, 0, 0); } while (0)
; #define PG8_LDA(dst, b, h) do { _Pragma("unroll") for (int m = 0; m < 4; ++m) _Pragma("unroll") for (int k = 0; k < 2; ++k) dst[m][k] = *(const PG8_LAS bf16x8*)(lds + PG8_SA(b, h) + aoff + m * 2048 + k * 1024); } while (0)
; #define PG8_LDB(dst, b, h) do { _Pragma("unroll") for (int n = 0; n < 2; ++n) _Pragma("unroll") for (int k = 0; k < 2; ++k) dst[n][k] = *(const PG8_LAS bf16x8*)(lds + PG8_SB(b, h) + boff + n * 2048 + k * 1024); } while (0)
; #define PG8_MMA(ai, bj, At, Bt) do { __builtin_amdgcn_s_setprio(1); _Pragma("unroll") for (int m = 0; m < 4; ++m) _Pragma("unroll") for (int n = 0; n < 2; ++n) _Pragma("unroll") for (int k = 0; k < 2; ++k) \
;         acc[ai][bj][m][n] = __builtin_amdgcn_mfma_f32_16x16x32_bf16(Bt[n][k], At[m][k], acc[ai][bj][m][n], 0, 0, 0); __builtin_amdgcn_s_setprio(0); } while (0)
; #define PG8_WAIT_V(n) asm volatile("s_waitcnt vmcnt(" #n ")" ::: "memory")
; #define PG8_WAIT_L(n) asm volatile("s_waitcnt lgkmcnt(" #n ")" ::: "memory")
; #define PG8_BAR __builtin_amdgcn_s_barrier()
; template <class Epi, class Sched, bool ALIGN_EPI = false, bool SP2 = false>
; __device__ __forceinline__ void gemm_phase(PG8_LAS unsigned char* lds, const Gemm g, const Sched& S, const Epi& E) {
;     ...
;         for (int t = 0; t < nt; t += 2) {
;             const bool last = (t == nt - 2);
;             const char* a1 = cA + (size_t)(t + 1) * kstep;
;             const char* a2 = last ? nA : cA + (size_t)(t + 2) * kstep; const char* b2 = last ? nB : cB + (size_t)(t + 2) * kstep;
;             const char* a3 = a2 + kstep; const char* b3 = b2 + kstep;
;     ...
;             PG8_LDB(B0, 1, 0); PG8_LDB(B1, 1, 1); PG8_SCHED; PG8_LDA(At, 1, 0); PG8_STAGE(PG8_SA(0, 1), a2 + hstep, voffA);
;             PG8_WAIT_V(8); PG8_WAIT_L(0); PG8_BAR; PG8_MMA(0, 0, At, B0); PG8_MMA(0, 1, At, B1); PG8_BAR; PG8_SCHED;
;             PG8_LDA(At, 1, 1); PG8_STAGE(PG8_SB(1, 0), b3, voffB); PG8_STAGE(PG8_SB(1, 1), b3 + hstep, voffB); PG8_STAGE(PG8_SA(1, 0), a3, voffA);
;             PG8_WAIT_V(8); PG8_WAIT_L(0); PG8_BAR; PG8_MMA(1, 0, At, B0); PG8_MMA(1, 1, At, B1); PG8_BAR; PG8_SCHED;
	ds_read_b128 v[152:155], v158
	ds_read_b128 v[164:167], v158 offset:1024
	ds_read_b128 v[168:171], v158 offset:2048
	ds_read_b128 v[172:175], v158 offset:3072
	ds_read_b128 v[176:179], v159
	ds_read_b128 v[180:183], v159 offset:1024
	ds_read_b128 v[184:187], v159 offset:2048
	ds_read_b128 v[188:191], v159 offset:3072
	s_add_u32 s36, s88, 0x80000
	s_addc_u32 s37, s89, 0
	s_mov_b32 m0, s13
	ds_read_b128 v[192:195], v157 offset:32768
	ds_read_b128 v[196:199], v157 offset:33792
	ds_read_b128 v[200:203], v157 offset:34816
	ds_read_b128 v[208:211], v157 offset:35840
	ds_read_b128 v[212:215], v157 offset:36864
	ds_read_b128 v[216:219], v157 offset:37888
	ds_read_b128 v[220:223], v157 offset:38912
	ds_read_b128 v[224:227], v157 offset:39936
	global_load_lds_dwordx4 v130, s[36:37]
	s_mov_b32 m0, s14
	s_nop 0
	global_load_lds_dwordx4 v134, s[36:37]
	s_waitcnt vmcnt(8)
	s_waitcnt lgkmcnt(0)
	s_barrier
	s_setprio 1
	s_waitcnt lgkmcnt(0)
	v_mfma_f32_16x16x32_bf16 v[126:129], v[152:155], v[192:195], v[126:129]
	v_mfma_f32_16x16x32_bf16 v[122:125], v[168:171], v[192:195], v[122:125]
	v_mfma_f32_16x16x32_bf16 v[110:113], v[152:155], v[200:203], v[110:113]
	v_mfma_f32_16x16x32_bf16 v[106:109], v[168:171], v[200:203], v[106:109]
	v_mfma_f32_16x16x32_bf16 v[94:97], v[152:155], v[212:215], v[94:97]
	v_mfma_f32_16x16x32_bf16 v[90:93], v[168:171], v[212:215], v[90:93]
	v_mfma_f32_16x16x32_bf16 v[78:81], v[152:155], v[220:223], v[78:81]
	v_mfma_f32_16x16x32_bf16 v[74:77], v[168:171], v[220:223], v[74:77]
	v_mfma_f32_16x16x32_bf16 v[126:129], v[164:167], v[196:199], v[126:129]
	v_mfma_f32_16x16x32_bf16 v[122:125], v[172:175], v[196:199], v[122:125]
	v_mfma_f32_16x16x32_bf16 v[110:113], v[164:167], v[208:211], v[110:113]
	v_mfma_f32_16x16x32_bf16 v[106:109], v[172:175], v[208:211], v[106:109]
	v_mfma_f32_16x16x32_bf16 v[94:97], v[164:167], v[216:219], v[94:97]
	v_mfma_f32_16x16x32_bf16 v[90:93], v[172:175], v[216:219], v[90:93]
	v_mfma_f32_16x16x32_bf16 v[78:81], v[164:167], v[224:227], v[78:81]
	v_mfma_f32_16x16x32_bf16 v[74:77], v[172:175], v[224:227], v[74:77]
	s_setprio 0
	s_setprio 1
	v_mfma_f32_16x16x32_bf16 v[118:121], v[176:179], v[192:195], v[118:121]
	v_mfma_f32_16x16x32_bf16 v[114:117], v[184:187], v[192:195], v[114:117]
	v_mfma_f32_16x16x32_bf16 v[102:105], v[176:179], v[200:203], v[102:105]
	v_mfma_f32_16x16x32_bf16 v[98:101], v[184:187], v[200:203], v[98:101]
	v_mfma_f32_16x16x32_bf16 v[86:89], v[176:179], v[212:215], v[86:89]
	v_mfma_f32_16x16x32_bf16 v[82:85], v[184:187], v[212:215], v[82:85]
	v_mfma_f32_16x16x32_bf16 v[70:73], v[176:179], v[220:223], v[70:73]
	v_mfma_f32_16x16x32_bf16 v[66:69], v[184:187], v[220:223], v[66:69]
	v_mfma_f32_16x16x32_bf16 v[118:121], v[180:183], v[196:199], v[118:121]
	v_mfma_f32_16x16x32_bf16 v[114:117], v[188:191], v[196:199], v[114:117]
	v_mfma_f32_16x16x32_bf16 v[102:105], v[180:183], v[208:211], v[102:105]
	v_mfma_f32_16x16x32_bf16 v[98:101], v[188:191], v[208:211], v[98:101]
	v_mfma_f32_16x16x32_bf16 v[86:89], v[180:183], v[216:219], v[86:89]
	v_mfma_f32_16x16x32_bf16 v[82:85], v[188:191], v[216:219], v[82:85]
	v_mfma_f32_16x16x32_bf16 v[70:73], v[180:183], v[224:227], v[70:73]
	v_mfma_f32_16x16x32_bf16 v[66:69], v[188:191], v[224:227], v[66:69]
	s_setprio 0
	s_barrier
	s_add_i32 s36, s61, s8
	s_nop 0
	s_mov_b32 m0, s36
	ds_read_b128 v[192:195], v157 offset:49152
	ds_read_b128 v[196:199], v157 offset:50176
	ds_read_b128 v[200:203], v157 offset:51200
	ds_read_b128 v[208:211], v157 offset:52224
	ds_read_b128 v[212:215], v157 offset:53248
	ds_read_b128 v[216:219], v157 offset:54272
	ds_read_b128 v[220:223], v157 offset:55296
	ds_read_b128 v[224:227], v157 offset:56320
	global_load_lds_dwordx4 v132, s[98:99]
	s_add_i32 m0, s36, 0x2000
	s_add_u32 s36, s86, 0x80080
	s_nop 0
	s_addc_u32 s37, s87, 0
	s_add_i32 s40, s62, s8
	global_load_lds_dwordx4 v136, s[98:99]
	s_mov_b32 m0, s40
	s_nop 0
	global_load_lds_dwordx4 v132, s[36:37]
	s_add_i32 m0, s40, 0x2000
	s_nop 0
	global_load_lds_dwordx4 v136, s[36:37]
	s_nop 0
	s_mov_b32 m0, s15
	s_nop 0
	global_load_lds_dwordx4 v130, s[100:101]
	s_nop 0
	s_mov_b32 m0, s16
	s_nop 0
	global_load_lds_dwordx4 v134, s[100:101]
	s_waitcnt vmcnt(8)
	s_waitcnt lgkmcnt(0)
	s_barrier
	s_setprio 1
	s_waitcnt lgkmcnt(0)
	v_mfma_f32_16x16x32_bf16 v[62:65], v[152:155], v[192:195], v[62:65]
	v_mfma_f32_16x16x32_bf16 v[58:61], v[168:171], v[192:195], v[58:61]
	v_mfma_f32_16x16x32_bf16 v[46:49], v[152:155], v[200:203], v[46:49]
	v_mfma_f32_16x16x32_bf16 v[42:45], v[168:171], v[200:203], v[42:45]
	v_mfma_f32_16x16x32_bf16 v[30:33], v[152:155], v[212:215], v[30:33]
	v_mfma_f32_16x16x32_bf16 v[26:29], v[168:171], v[212:215], v[26:29]
	v_mfma_f32_16x16x32_bf16 v[14:17], v[152:155], v[220:223], v[14:17]
	v_mfma_f32_16x16x32_bf16 v[10:13], v[168:171], v[220:223], v[10:13]
	v_mfma_f32_16x16x32_bf16 v[62:65], v[164:167], v[196:199], v[62:65]
	v_mfma_f32_16x16x32_bf16 v[58:61], v[172:175], v[196:199], v[58:61]
	v_mfma_f32_16x16x32_bf16 v[46:49], v[164:167], v[208:211], v[46:49]
	v_mfma_f32_16x16x32_bf16 v[42:45], v[172:175], v[208:211], v[42:45]
	v_mfma_f32_16x16x32_bf16 v[30:33], v[164:167], v[216:219], v[30:33]
	v_mfma_f32_16x16x32_bf16 v[26:29], v[172:175], v[216:219], v[26:29]
	v_mfma_f32_16x16x32_bf16 v[14:17], v[164:167], v[224:227], v[14:17]
	v_mfma_f32_16x16x32_bf16 v[10:13], v[172:175], v[224:227], v[10:13]
	s_setprio 0
	s_setprio 1
	v_mfma_f32_16x16x32_bf16 v[54:57], v[176:179], v[192:195], v[54:57]
	v_mfma_f32_16x16x32_bf16 v[50:53], v[184:187], v[192:195], v[50:53]
	v_mfma_f32_16x16x32_bf16 v[38:41], v[176:179], v[200:203], v[38:41]
	v_mfma_f32_16x16x32_bf16 v[34:37], v[184:187], v[200:203], v[34:37]
	v_mfma_f32_16x16x32_bf16 v[22:25], v[176:179], v[212:215], v[22:25]
	v_mfma_f32_16x16x32_bf16 v[18:21], v[184:187], v[212:215], v[18:21]
	v_mfma_f32_16x16x32_bf16 v[6:9], v[176:179], v[220:223], v[6:9]
	v_mfma_f32_16x16x32_bf16 v[2:5], v[184:187], v[220:223], v[2:5]
	v_mfma_f32_16x16x32_bf16 v[54:57], v[180:183], v[196:199], v[54:57]
	v_mfma_f32_16x16x32_bf16 v[50:53], v[188:191], v[196:199], v[50:53]
	v_mfma_f32_16x16x32_bf16 v[38:41], v[180:183], v[208:211], v[38:41]
	v_mfma_f32_16x16x32_bf16 v[34:37], v[188:191], v[208:211], v[34:37]
	v_mfma_f32_16x16x32_bf16 v[22:25], v[180:183], v[216:219], v[22:25]
	v_mfma_f32_16x16x32_bf16 v[18:21], v[188:191], v[216:219], v[18:21]
	v_mfma_f32_16x16x32_bf16 v[6:9], v[180:183], v[224:227], v[6:9]
	v_mfma_f32_16x16x32_bf16 v[2:5], v[188:191], v[224:227], v[2:5]
	s_setprio 0
	s_barrier
	s_add_i32 s97, s97, 2
	s_add_u32 s84, s84, 0x100
	s_addc_u32 s85, s85, 0
	s_add_u32 s81, s81, 0x100
	s_addc_u32 s83, s83, 0
	s_cmp_gt_u32 s97, 29
	s_cbranch_scc0 .LBB0_120
	s_and_b64 vcc, exec, s[50:51]
	s_cbranch_vccnz .LBB0_125
	v_lshl_add_u32 v152, s82, 8, v1
	s_cmp_gt_i32 s80, 2
	s_mov_b64 s[82:83], -1
	s_cbranch_scc1 .LBB0_126

; #define PG8_STAGE(bufoff, gbase, voff) do { _Pragma("unroll") for (int _i = 0; _i < 2; ++_i) \
;         __builtin_amdgcn_global_load_lds((const unsigned*)((const char*)(gbase) + (voff)[_i]), (PG8_LAS unsigned*)(lds + (bufoff) + ldsw + _i * 8192), 16, 0, 0); } while (0)
; #define PG8_LDA(dst, b, h) do { _Pragma("unroll") for (int m = 0; m < 4; ++m) _Pragma("unroll") for (int k = 0; k < 2; ++k) dst[m][k] = *(const PG8_LAS bf16x8*)(lds + PG8_SA(b, h) + aoff + m * 2048 + k * 1024); } while (0)
; #define PG8_LDB(dst, b, h) do { _Pragma("unroll") for (int n = 0; n < 2; ++n) _Pragma("unroll") for (int k = 0; k < 2; ++k) dst[n][k] = *(const PG8_LAS bf16x8*)(lds + PG8_SB(b, h) + boff + n * 2048 + k * 1024); } while (0)
; #define PG8_MMA(ai, bj, At, Bt) do { __builtin_amdgcn_s_setprio(1); _Pragma("unroll") for (int m = 0; m < 4; ++m) _Pragma("unroll") for (int n = 0; n < 2; ++n) _Pragma("unroll") for (int k = 0; k < 2; ++k) \
;         acc[ai][bj][m][n] = __builtin_amdgcn_mfma_f32_16x16x32_bf16(Bt[n][k], At[m][k], acc[ai][bj][m][n], 0, 0, 0); __builtin_amdgcn_s_setprio(0); } while (0)
; #define PG8_WAIT_V(n) asm volatile("s_waitcnt vmcnt(" #n ")" ::: "memory")
; #define PG8_WAIT_L(n) asm volatile("s_waitcnt lgkmcnt(" #n ")" ::: "memory")
; #define PG8_BAR __builtin_amdgcn_s_barrier()
; #define PG8_SCHED __builtin_amdgcn_sched_barrier(0)
; template <class Epi, class Sched, bool ALIGN_EPI = false, bool SP2 = false>
; __device__ __forceinline__ void gemm_phase(PG8_LAS unsigned char* lds, const Gemm g, const Sched& S, const Epi& E) {
;     ...
;             PG8_LDB(B0, 0, 0); PG8_LDB(B1, 0, 1); PG8_SCHED; PG8_LDA(At, 0, 0); PG8_STAGE(PG8_SA(1, 1), a1 + hstep, voffA);
;             PG8_WAIT_V(8); PG8_WAIT_L(0); PG8_BAR; PG8_MMA(0, 0, At, B0); PG8_MMA(0, 1, At, B1); PG8_BAR; PG8_SCHED;
;             PG8_LDA(At, 0, 1); PG8_STAGE(PG8_SB(0, 0), b2, voffB); PG8_STAGE(PG8_SB(0, 1), b2 + hstep, voffB); PG8_STAGE(PG8_SA(0, 0), a2, voffA);
;             PG8_WAIT_V(8); PG8_WAIT_L(0); PG8_BAR; PG8_MMA(1, 0, At, B0); PG8_MMA(1, 1, At, B1); PG8_BAR; PG8_SCHED;
.LBB0_716:
	ds_read_b128 v[148:151], v154
	ds_read_b128 v[164:167], v154 offset:1024
	ds_read_b128 v[168:171], v154 offset:2048
	ds_read_b128 v[172:175], v154 offset:3072
	ds_read_b128 v[176:179], v155
	ds_read_b128 v[180:183], v155 offset:1024
	ds_read_b128 v[184:187], v155 offset:2048
	ds_read_b128 v[188:191], v155 offset:3072
	s_add_u32 s68, s66, 0xfff80080
	s_addc_u32 s69, s67, -1
	s_cmp_eq_u32 s78, 28
	s_cselect_b32 s71, s47, s69
	s_cselect_b32 s70, s74, s68
	s_cselect_b32 s69, s45, s77
	s_cselect_b32 s68, s75, s76
	s_add_i32 m0, s13, 0xc000
	ds_read_b128 v[192:195], v156
	ds_read_b128 v[196:199], v156 offset:1024
	ds_read_b128 v[200:203], v156 offset:2048
	ds_read_b128 v[208:211], v156 offset:3072
	ds_read_b128 v[212:215], v156 offset:4096
	ds_read_b128 v[216:219], v156 offset:5120
	ds_read_b128 v[220:223], v156 offset:6144
	ds_read_b128 v[224:227], v156 offset:7168
	global_load_lds_dwordx4 v140, s[66:67]
	s_add_i32 m0, s13, 0xe000
	s_nop 0
	global_load_lds_dwordx4 v142, s[66:67]
	s_waitcnt vmcnt(8)
	s_waitcnt lgkmcnt(0)
	s_barrier
	s_setprio 1
	s_waitcnt lgkmcnt(0)
	v_mfma_f32_16x16x32_bf16 v[126:129], v[148:151], v[192:195], v[126:129]
	v_mfma_f32_16x16x32_bf16 v[122:125], v[168:171], v[192:195], v[122:125]
	v_mfma_f32_16x16x32_bf16 v[110:113], v[148:151], v[200:203], v[110:113]
	v_mfma_f32_16x16x32_bf16 v[106:109], v[168:171], v[200:203], v[106:109]
	v_mfma_f32_16x16x32_bf16 v[94:97], v[148:151], v[212:215], v[94:97]
	v_mfma_f32_16x16x32_bf16 v[90:93], v[168:171], v[212:215], v[90:93]
	v_mfma_f32_16x16x32_bf16 v[78:81], v[148:151], v[220:223], v[78:81]
	v_mfma_f32_16x16x32_bf16 v[74:77], v[168:171], v[220:223], v[74:77]
	v_mfma_f32_16x16x32_bf16 v[126:129], v[164:167], v[196:199], v[126:129]
	v_mfma_f32_16x16x32_bf16 v[122:125], v[172:175], v[196:199], v[122:125]
	v_mfma_f32_16x16x32_bf16 v[110:113], v[164:167], v[208:211], v[110:113]
	v_mfma_f32_16x16x32_bf16 v[106:109], v[172:175], v[208:211], v[106:109]
	v_mfma_f32_16x16x32_bf16 v[94:97], v[164:167], v[216:219], v[94:97]
	v_mfma_f32_16x16x32_bf16 v[90:93], v[172:175], v[216:219], v[90:93]
	v_mfma_f32_16x16x32_bf16 v[78:81], v[164:167], v[224:227], v[78:81]
	v_mfma_f32_16x16x32_bf16 v[74:77], v[172:175], v[224:227], v[74:77]
	s_setprio 0
	s_setprio 1
	v_mfma_f32_16x16x32_bf16 v[118:121], v[176:179], v[192:195], v[118:121]
	v_mfma_f32_16x16x32_bf16 v[114:117], v[184:187], v[192:195], v[114:117]
	v_mfma_f32_16x16x32_bf16 v[102:105], v[176:179], v[200:203], v[102:105]
	v_mfma_f32_16x16x32_bf16 v[98:101], v[184:187], v[200:203], v[98:101]
	v_mfma_f32_16x16x32_bf16 v[86:89], v[176:179], v[212:215], v[86:89]
	v_mfma_f32_16x16x32_bf16 v[82:85], v[184:187], v[212:215], v[82:85]
	v_mfma_f32_16x16x32_bf16 v[70:73], v[176:179], v[220:223], v[70:73]
	v_mfma_f32_16x16x32_bf16 v[66:69], v[184:187], v[220:223], v[66:69]
	v_mfma_f32_16x16x32_bf16 v[118:121], v[180:183], v[196:199], v[118:121]
	v_mfma_f32_16x16x32_bf16 v[114:117], v[188:191], v[196:199], v[114:117]
	v_mfma_f32_16x16x32_bf16 v[102:105], v[180:183], v[208:211], v[102:105]
	v_mfma_f32_16x16x32_bf16 v[98:101], v[188:191], v[208:211], v[98:101]
	v_mfma_f32_16x16x32_bf16 v[86:89], v[180:183], v[216:219], v[86:89]
	v_mfma_f32_16x16x32_bf16 v[82:85], v[188:191], v[216:219], v[82:85]
	v_mfma_f32_16x16x32_bf16 v[70:73], v[180:183], v[224:227], v[70:73]
	v_mfma_f32_16x16x32_bf16 v[66:69], v[188:191], v[224:227], v[66:69]
	s_setprio 0
	s_barrier
	s_add_u32 s98, s68, s6
	s_addc_u32 s99, s69, s7
	s_add_u32 s100, s70, s6
	s_addc_u32 s101, s71, s7
	s_add_i32 s79, s58, s12
	s_nop 0
	s_mov_b32 m0, s79
	ds_read_b128 v[192:195], v156 offset:16384
	ds_read_b128 v[196:199], v156 offset:17408
	ds_read_b128 v[200:203], v156 offset:18432
	ds_read_b128 v[208:211], v156 offset:19456
	ds_read_b128 v[212:215], v156 offset:20480
	ds_read_b128 v[216:219], v156 offset:21504
	ds_read_b128 v[220:223], v156 offset:22528
	ds_read_b128 v[224:227], v156 offset:23552
	global_load_lds_dwordx4 v132, s[68:69]
	s_add_i32 m0, s79, 0x2000
	s_add_u32 s80, s68, 0x80000
	s_nop 0
	s_addc_u32 s81, s69, 0
	s_add_i32 s79, s59, s12
	global_load_lds_dwordx4 v136, s[68:69]
	s_mov_b32 m0, s79
	s_nop 0
	global_load_lds_dwordx4 v132, s[80:81]
	s_add_i32 m0, s79, 0x2000
	s_nop 0
	global_load_lds_dwordx4 v136, s[80:81]
	s_nop 0
	s_mov_b32 m0, s13
	s_nop 0
	global_load_lds_dwordx4 v130, s[70:71]
	s_mov_b32 m0, s14
	s_nop 0
	global_load_lds_dwordx4 v134, s[70:71]
	s_waitcnt vmcnt(8)
	s_waitcnt lgkmcnt(0)
	s_barrier
	s_setprio 1
	s_waitcnt lgkmcnt(0)
	v_mfma_f32_16x16x32_bf16 v[62:65], v[148:151], v[192:195], v[62:65]
	v_mfma_f32_16x16x32_bf16 v[58:61], v[168:171], v[192:195], v[58:61]
	v_mfma_f32_16x16x32_bf16 v[46:49], v[148:151], v[200:203], v[46:49]
	v_mfma_f32_16x16x32_bf16 v[42:45], v[168:171], v[200:203], v[42:45]
	v_mfma_f32_16x16x32_bf16 v[30:33], v[148:151], v[212:215], v[30:33]
	v_mfma_f32_16x16x32_bf16 v[26:29], v[168:171], v[212:215], v[26:29]
	v_mfma_f32_16x16x32_bf16 v[14:17], v[148:151], v[220:223], v[14:17]
	v_mfma_f32_16x16x32_bf16 v[10:13], v[168:171], v[220:223], v[10:13]
	v_mfma_f32_16x16x32_bf16 v[62:65], v[164:167], v[196:199], v[62:65]
	v_mfma_f32_16x16x32_bf16 v[58:61], v[172:175], v[196:199], v[58:61]
	v_mfma_f32_16x16x32_bf16 v[46:49], v[164:167], v[208:211], v[46:49]
	v_mfma_f32_16x16x32_bf16 v[42:45], v[172:175], v[208:211], v[42:45]
	v_mfma_f32_16x16x32_bf16 v[30:33], v[164:167], v[216:219], v[30:33]
	v_mfma_f32_16x16x32_bf16 v[26:29], v[172:175], v[216:219], v[26:29]
	v_mfma_f32_16x16x32_bf16 v[14:17], v[164:167], v[224:227], v[14:17]
	v_mfma_f32_16x16x32_bf16 v[10:13], v[172:175], v[224:227], v[10:13]
	s_setprio 0
	s_setprio 1
	v_mfma_f32_16x16x32_bf16 v[54:57], v[176:179], v[192:195], v[54:57]
	v_mfma_f32_16x16x32_bf16 v[50:53], v[184:187], v[192:195], v[50:53]
	v_mfma_f32_16x16x32_bf16 v[38:41], v[176:179], v[200:203], v[38:41]
	v_mfma_f32_16x16x32_bf16 v[34:37], v[184:187], v[200:203], v[34:37]
	v_mfma_f32_16x16x32_bf16 v[22:25], v[176:179], v[212:215], v[22:25]
	v_mfma_f32_16x16x32_bf16 v[18:21], v[184:187], v[212:215], v[18:21]
	v_mfma_f32_16x16x32_bf16 v[6:9], v[176:179], v[220:223], v[6:9]
	v_mfma_f32_16x16x32_bf16 v[2:5], v[184:187], v[220:223], v[2:5]
	v_mfma_f32_16x16x32_bf16 v[54:57], v[180:183], v[196:199], v[54:57]
	v_mfma_f32_16x16x32_bf16 v[50:53], v[188:191], v[196:199], v[50:53]
	v_mfma_f32_16x16x32_bf16 v[38:41], v[180:183], v[208:211], v[38:41]
	v_mfma_f32_16x16x32_bf16 v[34:37], v[188:191], v[208:211], v[34:37]
	v_mfma_f32_16x16x32_bf16 v[22:25], v[180:183], v[216:219], v[22:25]
	v_mfma_f32_16x16x32_bf16 v[18:21], v[188:191], v[216:219], v[18:21]
	v_mfma_f32_16x16x32_bf16 v[6:9], v[180:183], v[224:227], v[6:9]
	v_mfma_f32_16x16x32_bf16 v[2:5], v[188:191], v[224:227], v[2:5]
	s_setprio 0
	s_barrier
; #define PG8_STAGE(bufoff, gbase, voff) do { _Pragma("unroll") for (int _i = 0; _i < 2; ++_i) \
;         __builtin_amdgcn_global_load_lds((const unsigned*)((const char*)(gbase) + (voff)[_i]), (PG8_LAS unsigned*)(lds + (bufoff) + ldsw + _i * 8192), 16, 0, 0); } while (0)
; #define PG8_LDA(dst, b, h) do { _Pragma("unroll") for (int m = 0; m < 4; ++m) _Pragma("unroll") for (int k = 0; k < 2; ++k) dst[m][k] = *(const PG8_LAS bf16x8*)(lds + PG8_SA(b, h) + aoff + m * 2048 + k * 1024); } while (0)
; #define PG8_LDB(dst, b, h) do { _Pragma("unroll") for (int n = 0; n < 2; ++n) _Pragma("unroll") for (int k = 0; k < 2; ++k) dst[n][k] = *(const PG8_LAS bf16x8*)(lds + PG8_SB(b, h) + boff + n * 2048 + k * 1024); } while (0)
; #define PG8_MMA(ai, bj, At, Bt) do { __builtin_amdgcn_s_setprio(1); _Pragma("unroll") for (int m = 0; m < 4; ++m) _Pragma("unroll") for (int n = 0; n < 2; ++n) _Pragma("unroll") for (int k = 0; k < 2; ++k) \
;         acc[ai][bj][m][n] = __builtin_amdgcn_mfma_f32_16x16x32_bf16(Bt[n][k], At[m][k], acc[ai][bj][m][n], 0, 0, 0); __builtin_amdgcn_s_setprio(0); } while (0)
; #define PG8_WAIT_V(n) asm volatile("s_waitcnt vmcnt(" #n ")" ::: "memory")
; #define PG8_WAIT_L(n) asm volatile("s_waitcnt lgkmcnt(" #n ")" ::: "memory")
; #define PG8_BAR __builtin_amdgcn_s_barrier()
; template <class Epi, class Sched, bool ALIGN_EPI = false, bool SP2 = false>
; __device__ __forceinline__ void gemm_phase(PG8_LAS unsigned char* lds, const Gemm g, const Sched& S, const Epi& E) {
;     ...
;         for (int t = 0; t < nt; t += 2) {
;             const bool last = (t == nt - 2);
;             const char* a1 = cA + (size_t)(t + 1) * kstep;
;             const char* a2 = last ? nA : cA + (size_t)(t + 2) * kstep; const char* b2 = last ? nB : cB + (size_t)(t + 2) * kstep;
;             const char* a3 = a2 + kstep; const char* b3 = b2 + kstep;
;     ...
;             PG8_LDB(B0, 1, 0); PG8_LDB(B1, 1, 1); PG8_SCHED; PG8_LDA(At, 1, 0); PG8_STAGE(PG8_SA(0, 1), a2 + hstep, voffA);
;             PG8_WAIT_V(8); PG8_WAIT_L(0); PG8_BAR; PG8_MMA(0, 0, At, B0); PG8_MMA(0, 1, At, B1); PG8_BAR; PG8_SCHED;
;             PG8_LDA(At, 1, 1); PG8_STAGE(PG8_SB(1, 0), b3, voffB); PG8_STAGE(PG8_SB(1, 1), b3 + hstep, voffB); PG8_STAGE(PG8_SA(1, 0), a3, voffA);
;             PG8_WAIT_V(8); PG8_WAIT_L(0); PG8_BAR; PG8_MMA(1, 0, At, B0); PG8_MMA(1, 1, At, B1); PG8_BAR; PG8_SCHED;
	ds_read_b128 v[148:151], v157
	ds_read_b128 v[164:167], v157 offset:1024
	ds_read_b128 v[168:171], v157 offset:2048
	ds_read_b128 v[172:175], v157 offset:3072
	ds_read_b128 v[176:179], v158
	ds_read_b128 v[180:183], v158 offset:1024
	ds_read_b128 v[184:187], v158 offset:2048
	ds_read_b128 v[188:191], v158 offset:3072
	s_add_u32 s70, s70, 0x80000
	s_addc_u32 s71, s71, 0
	s_mov_b32 m0, s15
	ds_read_b128 v[192:195], v156 offset:32768
	ds_read_b128 v[196:199], v156 offset:33792
	ds_read_b128 v[200:203], v156 offset:34816
	ds_read_b128 v[208:211], v156 offset:35840
	ds_read_b128 v[212:215], v156 offset:36864
	ds_read_b128 v[216:219], v156 offset:37888
	ds_read_b128 v[220:223], v156 offset:38912
	ds_read_b128 v[224:227], v156 offset:39936
	global_load_lds_dwordx4 v130, s[70:71]
	s_mov_b32 m0, s16
	s_nop 0
	global_load_lds_dwordx4 v134, s[70:71]
	s_waitcnt vmcnt(8)
	s_waitcnt lgkmcnt(0)
	s_barrier
	s_setprio 1
	s_waitcnt lgkmcnt(0)
	v_mfma_f32_16x16x32_bf16 v[126:129], v[148:151], v[192:195], v[126:129]
	v_mfma_f32_16x16x32_bf16 v[122:125], v[168:171], v[192:195], v[122:125]
	v_mfma_f32_16x16x32_bf16 v[110:113], v[148:151], v[200:203], v[110:113]
	v_mfma_f32_16x16x32_bf16 v[106:109], v[168:171], v[200:203], v[106:109]
	v_mfma_f32_16x16x32_bf16 v[94:97], v[148:151], v[212:215], v[94:97]
	v_mfma_f32_16x16x32_bf16 v[90:93], v[168:171], v[212:215], v[90:93]
	v_mfma_f32_16x16x32_bf16 v[78:81], v[148:151], v[220:223], v[78:81]
	v_mfma_f32_16x16x32_bf16 v[74:77], v[168:171], v[220:223], v[74:77]
	v_mfma_f32_16x16x32_bf16 v[126:129], v[164:167], v[196:199], v[126:129]
	v_mfma_f32_16x16x32_bf16 v[122:125], v[172:175], v[196:199], v[122:125]
	v_mfma_f32_16x16x32_bf16 v[110:113], v[164:167], v[208:211], v[110:113]
	v_mfma_f32_16x16x32_bf16 v[106:109], v[172:175], v[208:211], v[106:109]
	v_mfma_f32_16x16x32_bf16 v[94:97], v[164:167], v[216:219], v[94:97]
	v_mfma_f32_16x16x32_bf16 v[90:93], v[172:175], v[216:219], v[90:93]
	v_mfma_f32_16x16x32_bf16 v[78:81], v[164:167], v[224:227], v[78:81]
	v_mfma_f32_16x16x32_bf16 v[74:77], v[172:175], v[224:227], v[74:77]
	s_setprio 0
	s_setprio 1
	v_mfma_f32_16x16x32_bf16 v[118:121], v[176:179], v[192:195], v[118:121]
	v_mfma_f32_16x16x32_bf16 v[114:117], v[184:187], v[192:195], v[114:117]
	v_mfma_f32_16x16x32_bf16 v[102:105], v[176:179], v[200:203], v[102:105]
	v_mfma_f32_16x16x32_bf16 v[98:101], v[184:187], v[200:203], v[98:101]
	v_mfma_f32_16x16x32_bf16 v[86:89], v[176:179], v[212:215], v[86:89]
	v_mfma_f32_16x16x32_bf16 v[82:85], v[184:187], v[212:215], v[82:85]
	v_mfma_f32_16x16x32_bf16 v[70:73], v[176:179], v[220:223], v[70:73]
	v_mfma_f32_16x16x32_bf16 v[66:69], v[184:187], v[220:223], v[66:69]
	v_mfma_f32_16x16x32_bf16 v[118:121], v[180:183], v[196:199], v[118:121]
	v_mfma_f32_16x16x32_bf16 v[114:117], v[188:191], v[196:199], v[114:117]
	v_mfma_f32_16x16x32_bf16 v[102:105], v[180:183], v[208:211], v[102:105]
	v_mfma_f32_16x16x32_bf16 v[98:101], v[188:191], v[208:211], v[98:101]
	v_mfma_f32_16x16x32_bf16 v[86:89], v[180:183], v[216:219], v[86:89]
	v_mfma_f32_16x16x32_bf16 v[82:85], v[188:191], v[216:219], v[82:85]
	v_mfma_f32_16x16x32_bf16 v[70:73], v[180:183], v[224:227], v[70:73]
	v_mfma_f32_16x16x32_bf16 v[66:69], v[188:191], v[224:227], v[66:69]
	s_setprio 0
	s_barrier
	s_add_i32 s70, s61, s12
	s_nop 0
	s_mov_b32 m0, s70
	ds_read_b128 v[192:195], v156 offset:49152
	ds_read_b128 v[196:199], v156 offset:50176
	ds_read_b128 v[200:203], v156 offset:51200
	ds_read_b128 v[208:211], v156 offset:52224
	ds_read_b128 v[212:215], v156 offset:53248
	ds_read_b128 v[216:219], v156 offset:54272
	ds_read_b128 v[220:223], v156 offset:55296
	ds_read_b128 v[224:227], v156 offset:56320
	global_load_lds_dwordx4 v132, s[98:99]
	s_add_i32 m0, s70, 0x2000
	s_add_u32 s68, s68, 0x80080
	s_nop 0
	s_addc_u32 s69, s69, 0
	s_add_i32 s70, s62, s12
	global_load_lds_dwordx4 v136, s[98:99]
	s_mov_b32 m0, s70
	s_nop 0
	global_load_lds_dwordx4 v132, s[68:69]
	s_add_i32 m0, s70, 0x2000
	s_nop 0
	global_load_lds_dwordx4 v136, s[68:69]
	s_nop 0
	s_mov_b32 m0, s17
	s_nop 0
	global_load_lds_dwordx4 v130, s[100:101]
	s_nop 0
	s_mov_b32 m0, s33
	s_nop 0
	global_load_lds_dwordx4 v134, s[100:101]
	s_waitcnt vmcnt(8)
	s_waitcnt lgkmcnt(0)
	s_barrier
	s_setprio 1
	s_waitcnt lgkmcnt(0)
	v_mfma_f32_16x16x32_bf16 v[62:65], v[148:151], v[192:195], v[62:65]
	v_mfma_f32_16x16x32_bf16 v[58:61], v[168:171], v[192:195], v[58:61]
	v_mfma_f32_16x16x32_bf16 v[46:49], v[148:151], v[200:203], v[46:49]
	v_mfma_f32_16x16x32_bf16 v[42:45], v[168:171], v[200:203], v[42:45]
	v_mfma_f32_16x16x32_bf16 v[30:33], v[148:151], v[212:215], v[30:33]
	v_mfma_f32_16x16x32_bf16 v[26:29], v[168:171], v[212:215], v[26:29]
	v_mfma_f32_16x16x32_bf16 v[14:17], v[148:151], v[220:223], v[14:17]
	v_mfma_f32_16x16x32_bf16 v[10:13], v[168:171], v[220:223], v[10:13]
	v_mfma_f32_16x16x32_bf16 v[62:65], v[164:167], v[196:199], v[62:65]
	v_mfma_f32_16x16x32_bf16 v[58:61], v[172:175], v[196:199], v[58:61]
	v_mfma_f32_16x16x32_bf16 v[46:49], v[164:167], v[208:211], v[46:49]
	v_mfma_f32_16x16x32_bf16 v[42:45], v[172:175], v[208:211], v[42:45]
	v_mfma_f32_16x16x32_bf16 v[30:33], v[164:167], v[216:219], v[30:33]
	v_mfma_f32_16x16x32_bf16 v[26:29], v[172:175], v[216:219], v[26:29]
	v_mfma_f32_16x16x32_bf16 v[14:17], v[164:167], v[224:227], v[14:17]
	v_mfma_f32_16x16x32_bf16 v[10:13], v[172:175], v[224:227], v[10:13]
	s_setprio 0
	s_setprio 1
	v_mfma_f32_16x16x32_bf16 v[54:57], v[176:179], v[192:195], v[54:57]
	v_mfma_f32_16x16x32_bf16 v[50:53], v[184:187], v[192:195], v[50:53]
	v_mfma_f32_16x16x32_bf16 v[38:41], v[176:179], v[200:203], v[38:41]
	v_mfma_f32_16x16x32_bf16 v[34:37], v[184:187], v[200:203], v[34:37]
	v_mfma_f32_16x16x32_bf16 v[22:25], v[176:179], v[212:215], v[22:25]
	v_mfma_f32_16x16x32_bf16 v[18:21], v[184:187], v[212:215], v[18:21]
	v_mfma_f32_16x16x32_bf16 v[6:9], v[176:179], v[220:223], v[6:9]
	v_mfma_f32_16x16x32_bf16 v[2:5], v[184:187], v[220:223], v[2:5]
	v_mfma_f32_16x16x32_bf16 v[54:57], v[180:183], v[196:199], v[54:57]
	v_mfma_f32_16x16x32_bf16 v[50:53], v[188:191], v[196:199], v[50:53]
	v_mfma_f32_16x16x32_bf16 v[38:41], v[180:183], v[208:211], v[38:41]
	v_mfma_f32_16x16x32_bf16 v[34:37], v[188:191], v[208:211], v[34:37]
	v_mfma_f32_16x16x32_bf16 v[22:25], v[180:183], v[216:219], v[22:25]
	v_mfma_f32_16x16x32_bf16 v[18:21], v[188:191], v[216:219], v[18:21]
	v_mfma_f32_16x16x32_bf16 v[6:9], v[180:183], v[224:227], v[6:9]
	v_mfma_f32_16x16x32_bf16 v[2:5], v[188:191], v[224:227], v[2:5]
	s_setprio 0
	s_barrier
	s_add_i32 s78, s78, 2
	s_add_u32 s66, s66, 0x100
	s_addc_u32 s67, s67, 0
	s_add_u32 s76, s76, 0x100
	s_addc_u32 s77, s77, 0
	s_cmp_gt_u32 s78, 29
	s_cbranch_scc0 .LBB0_716
	s_and_b64 vcc, exec, s[36:37]
	s_cbranch_vccz .LBB0_719
	s_barrier

; #define PG8_STAGE(bufoff, gbase, voff) do { _Pragma("unroll") for (int _i = 0; _i < 2; ++_i) \
;         __builtin_amdgcn_global_load_lds((const unsigned*)((const char*)(gbase) + (voff)[_i]), (PG8_LAS unsigned*)(lds + (bufoff) + ldsw + _i * 8192), 16, 0, 0); } while (0)
; #define PG8_LDA(dst, b, h) do { _Pragma("unroll") for (int m = 0; m < 4; ++m) _Pragma("unroll") for (int k = 0; k < 2; ++k) dst[m][k] = *(const PG8_LAS bf16x8*)(lds + PG8_SA(b, h) + aoff + m * 2048 + k * 1024); } while (0)
; #define PG8_LDB(dst, b, h) do { _Pragma("unroll") for (int n = 0; n < 2; ++n) _Pragma("unroll") for (int k = 0; k < 2; ++k) dst[n][k] = *(const PG8_LAS bf16x8*)(lds + PG8_SB(b, h) + boff + n * 2048 + k * 1024); } while (0)
; #define PG8_MMA(ai, bj, At, Bt) do { __builtin_amdgcn_s_setprio(1); _Pragma("unroll") for (int m = 0; m < 4; ++m) _Pragma("unroll") for (int n = 0; n < 2; ++n) _Pragma("unroll") for (int k = 0; k < 2; ++k) \
;         acc[ai][bj][m][n] = __builtin_amdgcn_mfma_f32_16x16x32_bf16(Bt[n][k], At[m][k], acc[ai][bj][m][n], 0, 0, 0); __builtin_amdgcn_s_setprio(0); } while (0)
; #define PG8_WAIT_V(n) asm volatile("s_waitcnt vmcnt(" #n ")" ::: "memory")
; #define PG8_WAIT_L(n) asm volatile("s_waitcnt lgkmcnt(" #n ")" ::: "memory")
; #define PG8_BAR __builtin_amdgcn_s_barrier()
; #define PG8_SCHED __builtin_amdgcn_sched_barrier(0)
; template <class Epi, class Sched, bool ALIGN_EPI = false, bool SP2 = false>
; __device__ __forceinline__ void gemm_phase(PG8_LAS unsigned char* lds, const Gemm g, const Sched& S, const Epi& E) {
;     ...
;             PG8_LDB(B0, 0, 0); PG8_LDB(B1, 0, 1); PG8_SCHED; PG8_LDA(At, 0, 0); PG8_STAGE(PG8_SA(1, 1), a1 + hstep, voffA);
;             PG8_WAIT_V(8); PG8_WAIT_L(0); PG8_BAR; PG8_MMA(0, 0, At, B0); PG8_MMA(0, 1, At, B1); PG8_BAR; PG8_SCHED;
;             PG8_LDA(At, 0, 1); PG8_STAGE(PG8_SB(0, 0), b2, voffB); PG8_STAGE(PG8_SB(0, 1), b2 + hstep, voffB); PG8_STAGE(PG8_SA(0, 0), a2, voffA);
;             PG8_WAIT_V(8); PG8_WAIT_L(0); PG8_BAR; PG8_MMA(1, 0, At, B0); PG8_MMA(1, 1, At, B1); PG8_BAR; PG8_SCHED;
.LBB0_757:
	ds_read_b128 v[146:149], v159
	ds_read_b128 v[166:169], v159 offset:1024
	ds_read_b128 v[170:173], v159 offset:2048
	ds_read_b128 v[174:177], v159 offset:3072
	ds_read_b128 v[178:181], v160
	ds_read_b128 v[182:185], v160 offset:1024
	ds_read_b128 v[186:189], v160 offset:2048
	ds_read_b128 v[190:193], v160 offset:3072
	s_add_u32 s66, s64, 0xfff80080
	s_addc_u32 s67, s65, -1
	s_cmp_eq_u32 s71, 28
	s_cselect_b32 s69, s45, s67
	s_cselect_b32 s68, s61, s66
	s_cselect_b32 s67, s43, s70
	s_cselect_b32 s66, s62, s63
	s_add_i32 m0, s9, 0xc000
	ds_read_b128 v[194:197], v161
	ds_read_b128 v[198:201], v161 offset:1024
	ds_read_b128 v[202:205], v161 offset:2048
	ds_read_b128 v[208:211], v161 offset:3072
	ds_read_b128 v[212:215], v161 offset:4096
	ds_read_b128 v[216:219], v161 offset:5120
	ds_read_b128 v[220:223], v161 offset:6144
	ds_read_b128 v[224:227], v161 offset:7168
	global_load_lds_dwordx4 v138, s[64:65]
	s_add_i32 m0, s9, 0xe000
	s_nop 0
	global_load_lds_dwordx4 v140, s[64:65]
	s_waitcnt vmcnt(8)
	s_waitcnt lgkmcnt(0)
	s_barrier
	s_setprio 1
	s_waitcnt lgkmcnt(0)
	v_mfma_f32_16x16x32_bf16 v[126:129], v[146:149], v[194:197], v[126:129]
	v_mfma_f32_16x16x32_bf16 v[122:125], v[170:173], v[194:197], v[122:125]
	v_mfma_f32_16x16x32_bf16 v[110:113], v[146:149], v[202:205], v[110:113]
	v_mfma_f32_16x16x32_bf16 v[106:109], v[170:173], v[202:205], v[106:109]
	v_mfma_f32_16x16x32_bf16 v[94:97], v[146:149], v[212:215], v[94:97]
	v_mfma_f32_16x16x32_bf16 v[90:93], v[170:173], v[212:215], v[90:93]
	v_mfma_f32_16x16x32_bf16 v[78:81], v[146:149], v[220:223], v[78:81]
	v_mfma_f32_16x16x32_bf16 v[74:77], v[170:173], v[220:223], v[74:77]
	v_mfma_f32_16x16x32_bf16 v[126:129], v[166:169], v[198:201], v[126:129]
	v_mfma_f32_16x16x32_bf16 v[122:125], v[174:177], v[198:201], v[122:125]
	v_mfma_f32_16x16x32_bf16 v[110:113], v[166:169], v[208:211], v[110:113]
	v_mfma_f32_16x16x32_bf16 v[106:109], v[174:177], v[208:211], v[106:109]
	v_mfma_f32_16x16x32_bf16 v[94:97], v[166:169], v[216:219], v[94:97]
	v_mfma_f32_16x16x32_bf16 v[90:93], v[174:177], v[216:219], v[90:93]
	v_mfma_f32_16x16x32_bf16 v[78:81], v[166:169], v[224:227], v[78:81]
	v_mfma_f32_16x16x32_bf16 v[74:77], v[174:177], v[224:227], v[74:77]
	s_setprio 0
	s_setprio 1
	v_mfma_f32_16x16x32_bf16 v[118:121], v[178:181], v[194:197], v[118:121]
	v_mfma_f32_16x16x32_bf16 v[114:117], v[186:189], v[194:197], v[114:117]
	v_mfma_f32_16x16x32_bf16 v[102:105], v[178:181], v[202:205], v[102:105]
	v_mfma_f32_16x16x32_bf16 v[98:101], v[186:189], v[202:205], v[98:101]
	v_mfma_f32_16x16x32_bf16 v[86:89], v[178:181], v[212:215], v[86:89]
	v_mfma_f32_16x16x32_bf16 v[82:85], v[186:189], v[212:215], v[82:85]
	v_mfma_f32_16x16x32_bf16 v[70:73], v[178:181], v[220:223], v[70:73]
	v_mfma_f32_16x16x32_bf16 v[66:69], v[186:189], v[220:223], v[66:69]
	v_mfma_f32_16x16x32_bf16 v[118:121], v[182:185], v[198:201], v[118:121]
	v_mfma_f32_16x16x32_bf16 v[114:117], v[190:193], v[198:201], v[114:117]
	v_mfma_f32_16x16x32_bf16 v[102:105], v[182:185], v[208:211], v[102:105]
	v_mfma_f32_16x16x32_bf16 v[98:101], v[190:193], v[208:211], v[98:101]
	v_mfma_f32_16x16x32_bf16 v[86:89], v[182:185], v[216:219], v[86:89]
	v_mfma_f32_16x16x32_bf16 v[82:85], v[190:193], v[216:219], v[82:85]
	v_mfma_f32_16x16x32_bf16 v[70:73], v[182:185], v[224:227], v[70:73]
	v_mfma_f32_16x16x32_bf16 v[66:69], v[190:193], v[224:227], v[66:69]
	s_setprio 0
	s_barrier
	s_add_u32 s98, s66, s36
	s_addc_u32 s99, s67, s37
	s_add_u32 s100, s68, s36
	s_addc_u32 s101, s69, s37
	s_add_i32 s72, s35, s8
	s_nop 0
	s_mov_b32 m0, s72
	ds_read_b128 v[194:197], v161 offset:16384
	ds_read_b128 v[198:201], v161 offset:17408
	ds_read_b128 v[202:205], v161 offset:18432
	ds_read_b128 v[208:211], v161 offset:19456
	ds_read_b128 v[212:215], v161 offset:20480
	ds_read_b128 v[216:219], v161 offset:21504
	ds_read_b128 v[220:223], v161 offset:22528
	ds_read_b128 v[224:227], v161 offset:23552
	global_load_lds_dwordx4 v132, s[66:67]
	s_add_i32 m0, s72, 0x2000
	s_add_u32 s72, s66, 0x80000
	s_nop 0
	s_addc_u32 s73, s67, 0
	s_add_i32 s74, s51, s8
	global_load_lds_dwordx4 v136, s[66:67]
	s_mov_b32 m0, s74
	s_nop 0
	global_load_lds_dwordx4 v132, s[72:73]
	s_add_i32 m0, s74, 0x2000
	s_nop 0
	global_load_lds_dwordx4 v136, s[72:73]
	s_nop 0
	s_mov_b32 m0, s9
	s_nop 0
	global_load_lds_dwordx4 v130, s[68:69]
	s_mov_b32 m0, s12
	s_nop 0
	global_load_lds_dwordx4 v134, s[68:69]
	s_waitcnt vmcnt(8)
	s_waitcnt lgkmcnt(0)
	s_barrier
	s_setprio 1
	s_waitcnt lgkmcnt(0)
	v_mfma_f32_16x16x32_bf16 v[62:65], v[146:149], v[194:197], v[62:65]
	v_mfma_f32_16x16x32_bf16 v[58:61], v[170:173], v[194:197], v[58:61]
	v_mfma_f32_16x16x32_bf16 v[46:49], v[146:149], v[202:205], v[46:49]
	v_mfma_f32_16x16x32_bf16 v[42:45], v[170:173], v[202:205], v[42:45]
	v_mfma_f32_16x16x32_bf16 v[30:33], v[146:149], v[212:215], v[30:33]
	v_mfma_f32_16x16x32_bf16 v[26:29], v[170:173], v[212:215], v[26:29]
	v_mfma_f32_16x16x32_bf16 v[14:17], v[146:149], v[220:223], v[14:17]
	v_mfma_f32_16x16x32_bf16 v[10:13], v[170:173], v[220:223], v[10:13]
	v_mfma_f32_16x16x32_bf16 v[62:65], v[166:169], v[198:201], v[62:65]
	v_mfma_f32_16x16x32_bf16 v[58:61], v[174:177], v[198:201], v[58:61]
	v_mfma_f32_16x16x32_bf16 v[46:49], v[166:169], v[208:211], v[46:49]
	v_mfma_f32_16x16x32_bf16 v[42:45], v[174:177], v[208:211], v[42:45]
	v_mfma_f32_16x16x32_bf16 v[30:33], v[166:169], v[216:219], v[30:33]
	v_mfma_f32_16x16x32_bf16 v[26:29], v[174:177], v[216:219], v[26:29]
	v_mfma_f32_16x16x32_bf16 v[14:17], v[166:169], v[224:227], v[14:17]
	v_mfma_f32_16x16x32_bf16 v[10:13], v[174:177], v[224:227], v[10:13]
	s_setprio 0
	s_setprio 1
	v_mfma_f32_16x16x32_bf16 v[54:57], v[178:181], v[194:197], v[54:57]
	v_mfma_f32_16x16x32_bf16 v[50:53], v[186:189], v[194:197], v[50:53]
	v_mfma_f32_16x16x32_bf16 v[38:41], v[178:181], v[202:205], v[38:41]
	v_mfma_f32_16x16x32_bf16 v[34:37], v[186:189], v[202:205], v[34:37]
	v_mfma_f32_16x16x32_bf16 v[22:25], v[178:181], v[212:215], v[22:25]
	v_mfma_f32_16x16x32_bf16 v[18:21], v[186:189], v[212:215], v[18:21]
	v_mfma_f32_16x16x32_bf16 v[6:9], v[178:181], v[220:223], v[6:9]
	v_mfma_f32_16x16x32_bf16 v[2:5], v[186:189], v[220:223], v[2:5]
	v_mfma_f32_16x16x32_bf16 v[54:57], v[182:185], v[198:201], v[54:57]
	v_mfma_f32_16x16x32_bf16 v[50:53], v[190:193], v[198:201], v[50:53]
	v_mfma_f32_16x16x32_bf16 v[38:41], v[182:185], v[208:211], v[38:41]
	v_mfma_f32_16x16x32_bf16 v[34:37], v[190:193], v[208:211], v[34:37]
	v_mfma_f32_16x16x32_bf16 v[22:25], v[182:185], v[216:219], v[22:25]
	v_mfma_f32_16x16x32_bf16 v[18:21], v[190:193], v[216:219], v[18:21]
	v_mfma_f32_16x16x32_bf16 v[6:9], v[182:185], v[224:227], v[6:9]
	v_mfma_f32_16x16x32_bf16 v[2:5], v[190:193], v[224:227], v[2:5]
	s_setprio 0
	s_barrier
; #define PG8_STAGE(bufoff, gbase, voff) do { _Pragma("unroll") for (int _i = 0; _i < 2; ++_i) \
;         __builtin_amdgcn_global_load_lds((const unsigned*)((const char*)(gbase) + (voff)[_i]), (PG8_LAS unsigned*)(lds + (bufoff) + ldsw + _i * 8192), 16, 0, 0); } while (0)
; #define PG8_LDA(dst, b, h) do { _Pragma("unroll") for (int m = 0; m < 4; ++m) _Pragma("unroll") for (int k = 0; k < 2; ++k) dst[m][k] = *(const PG8_LAS bf16x8*)(lds + PG8_SA(b, h) + aoff + m * 2048 + k * 1024); } while (0)
; #define PG8_LDB(dst, b, h) do { _Pragma("unroll") for (int n = 0; n < 2; ++n) _Pragma("unroll") for (int k = 0; k < 2; ++k) dst[n][k] = *(const PG8_LAS bf16x8*)(lds + PG8_SB(b, h) + boff + n * 2048 + k * 1024); } while (0)
; #define PG8_MMA(ai, bj, At, Bt) do { __builtin_amdgcn_s_setprio(1); _Pragma("unroll") for (int m = 0; m < 4; ++m) _Pragma("unroll") for (int n = 0; n < 2; ++n) _Pragma("unroll") for (int k = 0; k < 2; ++k) \
;         acc[ai][bj][m][n] = __builtin_amdgcn_mfma_f32_16x16x32_bf16(Bt[n][k], At[m][k], acc[ai][bj][m][n], 0, 0, 0); __builtin_amdgcn_s_setprio(0); } while (0)
; #define PG8_WAIT_V(n) asm volatile("s_waitcnt vmcnt(" #n ")" ::: "memory")
; #define PG8_WAIT_L(n) asm volatile("s_waitcnt lgkmcnt(" #n ")" ::: "memory")
; #define PG8_BAR __builtin_amdgcn_s_barrier()
; template <class Epi, class Sched, bool ALIGN_EPI = false, bool SP2 = false>
; __device__ __forceinline__ void gemm_phase(PG8_LAS unsigned char* lds, const Gemm g, const Sched& S, const Epi& E) {
;     ...
;         for (int t = 0; t < nt; t += 2) {
;             const bool last = (t == nt - 2);
;             const char* a1 = cA + (size_t)(t + 1) * kstep;
;             const char* a2 = last ? nA : cA + (size_t)(t + 2) * kstep; const char* b2 = last ? nB : cB + (size_t)(t + 2) * kstep;
;             const char* a3 = a2 + kstep; const char* b3 = b2 + kstep;
;     ...
;             PG8_LDB(B0, 1, 0); PG8_LDB(B1, 1, 1); PG8_SCHED; PG8_LDA(At, 1, 0); PG8_STAGE(PG8_SA(0, 1), a2 + hstep, voffA);
;             PG8_WAIT_V(8); PG8_WAIT_L(0); PG8_BAR; PG8_MMA(0, 0, At, B0); PG8_MMA(0, 1, At, B1); PG8_BAR; PG8_SCHED;
;             PG8_LDA(At, 1, 1); PG8_STAGE(PG8_SB(1, 0), b3, voffB); PG8_STAGE(PG8_SB(1, 1), b3 + hstep, voffB); PG8_STAGE(PG8_SA(1, 0), a3, voffA);
;             PG8_WAIT_V(8); PG8_WAIT_L(0); PG8_BAR; PG8_MMA(1, 0, At, B0); PG8_MMA(1, 1, At, B1); PG8_BAR; PG8_SCHED;
	ds_read_b128 v[146:149], v163
	ds_read_b128 v[166:169], v163 offset:1024
	ds_read_b128 v[170:173], v163 offset:2048
	ds_read_b128 v[174:177], v163 offset:3072
	ds_read_b128 v[178:181], v164
	ds_read_b128 v[182:185], v164 offset:1024
	ds_read_b128 v[186:189], v164 offset:2048
	ds_read_b128 v[190:193], v164 offset:3072
	s_add_u32 s68, s68, 0x80000
	s_addc_u32 s69, s69, 0
	s_mov_b32 m0, s13
	ds_read_b128 v[194:197], v161 offset:32768
	ds_read_b128 v[198:201], v161 offset:33792
	ds_read_b128 v[202:205], v161 offset:34816
	ds_read_b128 v[208:211], v161 offset:35840
	ds_read_b128 v[212:215], v161 offset:36864
	ds_read_b128 v[216:219], v161 offset:37888
	ds_read_b128 v[220:223], v161 offset:38912
	ds_read_b128 v[224:227], v161 offset:39936
	global_load_lds_dwordx4 v130, s[68:69]
	s_mov_b32 m0, s14
	s_nop 0
	global_load_lds_dwordx4 v134, s[68:69]
	s_waitcnt vmcnt(8)
	s_waitcnt lgkmcnt(0)
	s_barrier
	s_setprio 1
	s_waitcnt lgkmcnt(0)
	v_mfma_f32_16x16x32_bf16 v[126:129], v[146:149], v[194:197], v[126:129]
	v_mfma_f32_16x16x32_bf16 v[122:125], v[170:173], v[194:197], v[122:125]
	v_mfma_f32_16x16x32_bf16 v[110:113], v[146:149], v[202:205], v[110:113]
	v_mfma_f32_16x16x32_bf16 v[106:109], v[170:173], v[202:205], v[106:109]
	v_mfma_f32_16x16x32_bf16 v[94:97], v[146:149], v[212:215], v[94:97]
	v_mfma_f32_16x16x32_bf16 v[90:93], v[170:173], v[212:215], v[90:93]
	v_mfma_f32_16x16x32_bf16 v[78:81], v[146:149], v[220:223], v[78:81]
	v_mfma_f32_16x16x32_bf16 v[74:77], v[170:173], v[220:223], v[74:77]
	v_mfma_f32_16x16x32_bf16 v[126:129], v[166:169], v[198:201], v[126:129]
	v_mfma_f32_16x16x32_bf16 v[122:125], v[174:177], v[198:201], v[122:125]
	v_mfma_f32_16x16x32_bf16 v[110:113], v[166:169], v[208:211], v[110:113]
	v_mfma_f32_16x16x32_bf16 v[106:109], v[174:177], v[208:211], v[106:109]
	v_mfma_f32_16x16x32_bf16 v[94:97], v[166:169], v[216:219], v[94:97]
	v_mfma_f32_16x16x32_bf16 v[90:93], v[174:177], v[216:219], v[90:93]
	v_mfma_f32_16x16x32_bf16 v[78:81], v[166:169], v[224:227], v[78:81]
	v_mfma_f32_16x16x32_bf16 v[74:77], v[174:177], v[224:227], v[74:77]
	s_setprio 0
	s_setprio 1
	v_mfma_f32_16x16x32_bf16 v[118:121], v[178:181], v[194:197], v[118:121]
	v_mfma_f32_16x16x32_bf16 v[114:117], v[186:189], v[194:197], v[114:117]
	v_mfma_f32_16x16x32_bf16 v[102:105], v[178:181], v[202:205], v[102:105]
	v_mfma_f32_16x16x32_bf16 v[98:101], v[186:189], v[202:205], v[98:101]
	v_mfma_f32_16x16x32_bf16 v[86:89], v[178:181], v[212:215], v[86:89]
	v_mfma_f32_16x16x32_bf16 v[82:85], v[186:189], v[212:215], v[82:85]
	v_mfma_f32_16x16x32_bf16 v[70:73], v[178:181], v[220:223], v[70:73]
	v_mfma_f32_16x16x32_bf16 v[66:69], v[186:189], v[220:223], v[66:69]
	v_mfma_f32_16x16x32_bf16 v[118:121], v[182:185], v[198:201], v[118:121]
	v_mfma_f32_16x16x32_bf16 v[114:117], v[190:193], v[198:201], v[114:117]
	v_mfma_f32_16x16x32_bf16 v[102:105], v[182:185], v[208:211], v[102:105]
	v_mfma_f32_16x16x32_bf16 v[98:101], v[190:193], v[208:211], v[98:101]
	v_mfma_f32_16x16x32_bf16 v[86:89], v[182:185], v[216:219], v[86:89]
	v_mfma_f32_16x16x32_bf16 v[82:85], v[190:193], v[216:219], v[82:85]
	v_mfma_f32_16x16x32_bf16 v[70:73], v[182:185], v[224:227], v[70:73]
	v_mfma_f32_16x16x32_bf16 v[66:69], v[190:193], v[224:227], v[66:69]
	s_setprio 0
	s_barrier
	s_add_i32 s68, s57, s8
	s_nop 0
	s_mov_b32 m0, s68
	ds_read_b128 v[194:197], v161 offset:49152
	ds_read_b128 v[198:201], v161 offset:50176
	ds_read_b128 v[202:205], v161 offset:51200
	ds_read_b128 v[208:211], v161 offset:52224
	ds_read_b128 v[212:215], v161 offset:53248
	ds_read_b128 v[216:219], v161 offset:54272
	ds_read_b128 v[220:223], v161 offset:55296
	ds_read_b128 v[224:227], v161 offset:56320
	global_load_lds_dwordx4 v132, s[98:99]
	s_add_i32 m0, s68, 0x2000
	s_add_u32 s66, s66, 0x80080
	s_nop 0
	s_addc_u32 s67, s67, 0
	s_add_i32 s68, s58, s8
	global_load_lds_dwordx4 v136, s[98:99]
	s_mov_b32 m0, s68
	s_nop 0
	global_load_lds_dwordx4 v132, s[66:67]
	s_add_i32 m0, s68, 0x2000
	s_nop 0
	global_load_lds_dwordx4 v136, s[66:67]
	s_nop 0
	s_mov_b32 m0, s15
	s_nop 0
	global_load_lds_dwordx4 v130, s[100:101]
	s_nop 0
	s_mov_b32 m0, s16
	s_nop 0
	global_load_lds_dwordx4 v134, s[100:101]
	s_waitcnt vmcnt(8)
	s_waitcnt lgkmcnt(0)
	s_barrier
	s_setprio 1
	s_waitcnt lgkmcnt(0)
	v_mfma_f32_16x16x32_bf16 v[62:65], v[146:149], v[194:197], v[62:65]
	v_mfma_f32_16x16x32_bf16 v[58:61], v[170:173], v[194:197], v[58:61]
	v_mfma_f32_16x16x32_bf16 v[46:49], v[146:149], v[202:205], v[46:49]
	v_mfma_f32_16x16x32_bf16 v[42:45], v[170:173], v[202:205], v[42:45]
	v_mfma_f32_16x16x32_bf16 v[30:33], v[146:149], v[212:215], v[30:33]
	v_mfma_f32_16x16x32_bf16 v[26:29], v[170:173], v[212:215], v[26:29]
	v_mfma_f32_16x16x32_bf16 v[14:17], v[146:149], v[220:223], v[14:17]
	v_mfma_f32_16x16x32_bf16 v[10:13], v[170:173], v[220:223], v[10:13]
	v_mfma_f32_16x16x32_bf16 v[62:65], v[166:169], v[198:201], v[62:65]
	v_mfma_f32_16x16x32_bf16 v[58:61], v[174:177], v[198:201], v[58:61]
	v_mfma_f32_16x16x32_bf16 v[46:49], v[166:169], v[208:211], v[46:49]
	v_mfma_f32_16x16x32_bf16 v[42:45], v[174:177], v[208:211], v[42:45]
	v_mfma_f32_16x16x32_bf16 v[30:33], v[166:169], v[216:219], v[30:33]
	v_mfma_f32_16x16x32_bf16 v[26:29], v[174:177], v[216:219], v[26:29]
	v_mfma_f32_16x16x32_bf16 v[14:17], v[166:169], v[224:227], v[14:17]
	v_mfma_f32_16x16x32_bf16 v[10:13], v[174:177], v[224:227], v[10:13]
	s_setprio 0
	s_setprio 1
	v_mfma_f32_16x16x32_bf16 v[54:57], v[178:181], v[194:197], v[54:57]
	v_mfma_f32_16x16x32_bf16 v[50:53], v[186:189], v[194:197], v[50:53]
	v_mfma_f32_16x16x32_bf16 v[38:41], v[178:181], v[202:205], v[38:41]
	v_mfma_f32_16x16x32_bf16 v[34:37], v[186:189], v[202:205], v[34:37]
	v_mfma_f32_16x16x32_bf16 v[22:25], v[178:181], v[212:215], v[22:25]
	v_mfma_f32_16x16x32_bf16 v[18:21], v[186:189], v[212:215], v[18:21]
	v_mfma_f32_16x16x32_bf16 v[6:9], v[178:181], v[220:223], v[6:9]
	v_mfma_f32_16x16x32_bf16 v[2:5], v[186:189], v[220:223], v[2:5]
	v_mfma_f32_16x16x32_bf16 v[54:57], v[182:185], v[198:201], v[54:57]
	v_mfma_f32_16x16x32_bf16 v[50:53], v[190:193], v[198:201], v[50:53]
	v_mfma_f32_16x16x32_bf16 v[38:41], v[182:185], v[208:211], v[38:41]
	v_mfma_f32_16x16x32_bf16 v[34:37], v[190:193], v[208:211], v[34:37]
	v_mfma_f32_16x16x32_bf16 v[22:25], v[182:185], v[216:219], v[22:25]
	v_mfma_f32_16x16x32_bf16 v[18:21], v[190:193], v[216:219], v[18:21]
	v_mfma_f32_16x16x32_bf16 v[6:9], v[182:185], v[224:227], v[6:9]
	v_mfma_f32_16x16x32_bf16 v[2:5], v[190:193], v[224:227], v[2:5]
	s_setprio 0
	s_barrier
	s_add_i32 s71, s71, 2
	s_add_u32 s64, s64, 0x100
	s_addc_u32 s65, s65, 0
	s_add_u32 s63, s63, 0x100
	s_addc_u32 s70, s70, 0
	s_cmp_gt_u32 s71, 29
	s_cbranch_scc0 .LBB0_757
	s_and_b64 vcc, exec, s[40:41]
	s_cbranch_vccz .LBB0_760
	s_barrier

; #define PG8_STAGE(bufoff, gbase, voff) do { _Pragma("unroll") for (int _i = 0; _i < 2; ++_i) \
;         __builtin_amdgcn_global_load_lds((const unsigned*)((const char*)(gbase) + (voff)[_i]), (PG8_LAS unsigned*)(lds + (bufoff) + ldsw + _i * 8192), 16, 0, 0); } while (0)
; #define PG8_LDA(dst, b, h) do { _Pragma("unroll") for (int m = 0; m < 4; ++m) _Pragma("unroll") for (int k = 0; k < 2; ++k) dst[m][k] = *(const PG8_LAS bf16x8*)(lds + PG8_SA(b, h) + aoff + m * 2048 + k * 1024); } while (0)
; #define PG8_LDB(dst, b, h) do { _Pragma("unroll") for (int n = 0; n < 2; ++n) _Pragma("unroll") for (int k = 0; k < 2; ++k) dst[n][k] = *(const PG8_LAS bf16x8*)(lds + PG8_SB(b, h) + boff + n * 2048 + k * 1024); } while (0)
; #define PG8_MMA(ai, bj, At, Bt) do { __builtin_amdgcn_s_setprio(1); _Pragma("unroll") for (int m = 0; m < 4; ++m) _Pragma("unroll") for (int n = 0; n < 2; ++n) _Pragma("unroll") for (int k = 0; k < 2; ++k) \
;         acc[ai][bj][m][n] = __builtin_amdgcn_mfma_f32_16x16x32_bf16(Bt[n][k], At[m][k], acc[ai][bj][m][n], 0, 0, 0); __builtin_amdgcn_s_setprio(0); } while (0)
; #define PG8_WAIT_V(n) asm volatile("s_waitcnt vmcnt(" #n ")" ::: "memory")
; #define PG8_WAIT_L(n) asm volatile("s_waitcnt lgkmcnt(" #n ")" ::: "memory")
; #define PG8_BAR __builtin_amdgcn_s_barrier()
; #define PG8_SCHED __builtin_amdgcn_sched_barrier(0)
; template <class Epi, class Sched, bool ALIGN_EPI = false, bool SP2 = false>
; __device__ __forceinline__ void gemm_phase(PG8_LAS unsigned char* lds, const Gemm g, const Sched& S, const Epi& E) {
;     ...
;             PG8_LDB(B0, 0, 0); PG8_LDB(B1, 0, 1); PG8_SCHED; PG8_LDA(At, 0, 0); PG8_STAGE(PG8_SA(1, 1), a1 + hstep, voffA);
;             PG8_WAIT_V(8); PG8_WAIT_L(0); PG8_BAR; PG8_MMA(0, 0, At, B0); PG8_MMA(0, 1, At, B1); PG8_BAR; PG8_SCHED;
;             PG8_LDA(At, 0, 1); PG8_STAGE(PG8_SB(0, 0), b2, voffB); PG8_STAGE(PG8_SB(0, 1), b2 + hstep, voffB); PG8_STAGE(PG8_SA(0, 0), a2, voffA);
;             PG8_WAIT_V(8); PG8_WAIT_L(0); PG8_BAR; PG8_MMA(1, 0, At, B0); PG8_MMA(1, 1, At, B1); PG8_BAR; PG8_SCHED;
.LBB0_781:
	ds_read_b128 v[146:149], v155
	ds_read_b128 v[150:153], v155 offset:1024
	ds_read_b128 v[164:167], v155 offset:2048
	ds_read_b128 v[168:171], v155 offset:3072
	ds_read_b128 v[172:175], v156
	ds_read_b128 v[176:179], v156 offset:1024
	ds_read_b128 v[180:183], v156 offset:2048
	ds_read_b128 v[184:187], v156 offset:3072
	s_add_u32 s64, s50, 0xfff80080
	s_addc_u32 s65, s51, -1
	s_cmp_eq_u32 s69, 28
	s_cselect_b32 s67, s43, s65
	s_cselect_b32 s66, s61, s64
	s_cselect_b32 s65, s41, s68
	s_cselect_b32 s64, s62, s63
	s_add_i32 m0, s9, 0xc000
	ds_read_b128 v[188:191], v157
	ds_read_b128 v[192:195], v157 offset:1024
	ds_read_b128 v[196:199], v157 offset:2048
	ds_read_b128 v[200:203], v157 offset:3072
	ds_read_b128 v[208:211], v157 offset:4096
	ds_read_b128 v[212:215], v157 offset:5120
	ds_read_b128 v[216:219], v157 offset:6144
	ds_read_b128 v[220:223], v157 offset:7168
	global_load_lds_dwordx4 v138, s[50:51]
	s_add_i32 m0, s9, 0xe000
	s_nop 0
	global_load_lds_dwordx4 v140, s[50:51]
	s_waitcnt vmcnt(8)
	s_waitcnt lgkmcnt(0)
	s_barrier
	s_setprio 1
	s_waitcnt lgkmcnt(0)
	v_mfma_f32_16x16x32_bf16 v[126:129], v[146:149], v[188:191], v[126:129]
	v_mfma_f32_16x16x32_bf16 v[122:125], v[164:167], v[188:191], v[122:125]
	v_mfma_f32_16x16x32_bf16 v[110:113], v[146:149], v[196:199], v[110:113]
	v_mfma_f32_16x16x32_bf16 v[106:109], v[164:167], v[196:199], v[106:109]
	v_mfma_f32_16x16x32_bf16 v[94:97], v[146:149], v[208:211], v[94:97]
	v_mfma_f32_16x16x32_bf16 v[90:93], v[164:167], v[208:211], v[90:93]
	v_mfma_f32_16x16x32_bf16 v[78:81], v[146:149], v[216:219], v[78:81]
	v_mfma_f32_16x16x32_bf16 v[74:77], v[164:167], v[216:219], v[74:77]
	v_mfma_f32_16x16x32_bf16 v[126:129], v[150:153], v[192:195], v[126:129]
	v_mfma_f32_16x16x32_bf16 v[122:125], v[168:171], v[192:195], v[122:125]
	v_mfma_f32_16x16x32_bf16 v[110:113], v[150:153], v[200:203], v[110:113]
	v_mfma_f32_16x16x32_bf16 v[106:109], v[168:171], v[200:203], v[106:109]
	v_mfma_f32_16x16x32_bf16 v[94:97], v[150:153], v[212:215], v[94:97]
	v_mfma_f32_16x16x32_bf16 v[90:93], v[168:171], v[212:215], v[90:93]
	v_mfma_f32_16x16x32_bf16 v[78:81], v[150:153], v[220:223], v[78:81]
	v_mfma_f32_16x16x32_bf16 v[74:77], v[168:171], v[220:223], v[74:77]
	s_setprio 0
	s_setprio 1
	v_mfma_f32_16x16x32_bf16 v[118:121], v[172:175], v[188:191], v[118:121]
	v_mfma_f32_16x16x32_bf16 v[114:117], v[180:183], v[188:191], v[114:117]
	v_mfma_f32_16x16x32_bf16 v[102:105], v[172:175], v[196:199], v[102:105]
	v_mfma_f32_16x16x32_bf16 v[98:101], v[180:183], v[196:199], v[98:101]
	v_mfma_f32_16x16x32_bf16 v[86:89], v[172:175], v[208:211], v[86:89]
	v_mfma_f32_16x16x32_bf16 v[82:85], v[180:183], v[208:211], v[82:85]
	v_mfma_f32_16x16x32_bf16 v[70:73], v[172:175], v[216:219], v[70:73]
	v_mfma_f32_16x16x32_bf16 v[66:69], v[180:183], v[216:219], v[66:69]
	v_mfma_f32_16x16x32_bf16 v[118:121], v[176:179], v[192:195], v[118:121]
	v_mfma_f32_16x16x32_bf16 v[114:117], v[184:187], v[192:195], v[114:117]
	v_mfma_f32_16x16x32_bf16 v[102:105], v[176:179], v[200:203], v[102:105]
	v_mfma_f32_16x16x32_bf16 v[98:101], v[184:187], v[200:203], v[98:101]
	v_mfma_f32_16x16x32_bf16 v[86:89], v[176:179], v[212:215], v[86:89]
	v_mfma_f32_16x16x32_bf16 v[82:85], v[184:187], v[212:215], v[82:85]
	v_mfma_f32_16x16x32_bf16 v[70:73], v[176:179], v[220:223], v[70:73]
	v_mfma_f32_16x16x32_bf16 v[66:69], v[184:187], v[220:223], v[66:69]
	s_setprio 0
	s_barrier
	s_add_u32 s98, s64, s22
	s_addc_u32 s99, s65, s23
	s_add_u32 s100, s66, s22
	s_addc_u32 s101, s67, s23
	s_add_i32 s70, s35, s8
	s_nop 0
	s_mov_b32 m0, s70
	ds_read_b128 v[188:191], v157 offset:16384
	ds_read_b128 v[192:195], v157 offset:17408
	ds_read_b128 v[196:199], v157 offset:18432
	ds_read_b128 v[200:203], v157 offset:19456
	ds_read_b128 v[208:211], v157 offset:20480
	ds_read_b128 v[212:215], v157 offset:21504
	ds_read_b128 v[216:219], v157 offset:22528
	ds_read_b128 v[220:223], v157 offset:23552
	global_load_lds_dwordx4 v132, s[64:65]
	s_add_i32 m0, s70, 0x2000
	s_add_u32 s70, s64, 0x80000
	s_nop 0
	s_addc_u32 s71, s65, 0
	s_add_i32 s72, s49, s8
	global_load_lds_dwordx4 v136, s[64:65]
	s_mov_b32 m0, s72
	s_nop 0
	global_load_lds_dwordx4 v132, s[70:71]
	s_add_i32 m0, s72, 0x2000
	s_nop 0
	global_load_lds_dwordx4 v136, s[70:71]
	s_nop 0
	s_mov_b32 m0, s9
	s_nop 0
	global_load_lds_dwordx4 v130, s[66:67]
	s_mov_b32 m0, s12
	s_nop 0
	global_load_lds_dwordx4 v134, s[66:67]
	s_waitcnt vmcnt(8)
	s_waitcnt lgkmcnt(0)
	s_barrier
	s_setprio 1
	s_waitcnt lgkmcnt(0)
	v_mfma_f32_16x16x32_bf16 v[62:65], v[146:149], v[188:191], v[62:65]
	v_mfma_f32_16x16x32_bf16 v[58:61], v[164:167], v[188:191], v[58:61]
	v_mfma_f32_16x16x32_bf16 v[46:49], v[146:149], v[196:199], v[46:49]
	v_mfma_f32_16x16x32_bf16 v[42:45], v[164:167], v[196:199], v[42:45]
	v_mfma_f32_16x16x32_bf16 v[30:33], v[146:149], v[208:211], v[30:33]
	v_mfma_f32_16x16x32_bf16 v[26:29], v[164:167], v[208:211], v[26:29]
	v_mfma_f32_16x16x32_bf16 v[14:17], v[146:149], v[216:219], v[14:17]
	v_mfma_f32_16x16x32_bf16 v[10:13], v[164:167], v[216:219], v[10:13]
	v_mfma_f32_16x16x32_bf16 v[62:65], v[150:153], v[192:195], v[62:65]
	v_mfma_f32_16x16x32_bf16 v[58:61], v[168:171], v[192:195], v[58:61]
	v_mfma_f32_16x16x32_bf16 v[46:49], v[150:153], v[200:203], v[46:49]
	v_mfma_f32_16x16x32_bf16 v[42:45], v[168:171], v[200:203], v[42:45]
	v_mfma_f32_16x16x32_bf16 v[30:33], v[150:153], v[212:215], v[30:33]
	v_mfma_f32_16x16x32_bf16 v[26:29], v[168:171], v[212:215], v[26:29]
	v_mfma_f32_16x16x32_bf16 v[14:17], v[150:153], v[220:223], v[14:17]
	v_mfma_f32_16x16x32_bf16 v[10:13], v[168:171], v[220:223], v[10:13]
	s_setprio 0
	s_setprio 1
	v_mfma_f32_16x16x32_bf16 v[54:57], v[172:175], v[188:191], v[54:57]
	v_mfma_f32_16x16x32_bf16 v[50:53], v[180:183], v[188:191], v[50:53]
	v_mfma_f32_16x16x32_bf16 v[38:41], v[172:175], v[196:199], v[38:41]
	v_mfma_f32_16x16x32_bf16 v[34:37], v[180:183], v[196:199], v[34:37]
	v_mfma_f32_16x16x32_bf16 v[22:25], v[172:175], v[208:211], v[22:25]
	v_mfma_f32_16x16x32_bf16 v[18:21], v[180:183], v[208:211], v[18:21]
	v_mfma_f32_16x16x32_bf16 v[6:9], v[172:175], v[216:219], v[6:9]
	v_mfma_f32_16x16x32_bf16 v[2:5], v[180:183], v[216:219], v[2:5]
	v_mfma_f32_16x16x32_bf16 v[54:57], v[176:179], v[192:195], v[54:57]
	v_mfma_f32_16x16x32_bf16 v[50:53], v[184:187], v[192:195], v[50:53]
	v_mfma_f32_16x16x32_bf16 v[38:41], v[176:179], v[200:203], v[38:41]
	v_mfma_f32_16x16x32_bf16 v[34:37], v[184:187], v[200:203], v[34:37]
	v_mfma_f32_16x16x32_bf16 v[22:25], v[176:179], v[212:215], v[22:25]
	v_mfma_f32_16x16x32_bf16 v[18:21], v[184:187], v[212:215], v[18:21]
	v_mfma_f32_16x16x32_bf16 v[6:9], v[176:179], v[220:223], v[6:9]
	v_mfma_f32_16x16x32_bf16 v[2:5], v[184:187], v[220:223], v[2:5]
	s_setprio 0
	s_barrier
; #define PG8_STAGE(bufoff, gbase, voff) do { _Pragma("unroll") for (int _i = 0; _i < 2; ++_i) \
;         __builtin_amdgcn_global_load_lds((const unsigned*)((const char*)(gbase) + (voff)[_i]), (PG8_LAS unsigned*)(lds + (bufoff) + ldsw + _i * 8192), 16, 0, 0); } while (0)
; #define PG8_LDA(dst, b, h) do { _Pragma("unroll") for (int m = 0; m < 4; ++m) _Pragma("unroll") for (int k = 0; k < 2; ++k) dst[m][k] = *(const PG8_LAS bf16x8*)(lds + PG8_SA(b, h) + aoff + m * 2048 + k * 1024); } while (0)
; #define PG8_LDB(dst, b, h) do { _Pragma("unroll") for (int n = 0; n < 2; ++n) _Pragma("unroll") for (int k = 0; k < 2; ++k) dst[n][k] = *(const PG8_LAS bf16x8*)(lds + PG8_SB(b, h) + boff + n * 2048 + k * 1024); } while (0)
; #define PG8_MMA(ai, bj, At, Bt) do { __builtin_amdgcn_s_setprio(1); _Pragma("unroll") for (int m = 0; m < 4; ++m) _Pragma("unroll") for (int n = 0; n < 2; ++n) _Pragma("unroll") for (int k = 0; k < 2; ++k) \
;         acc[ai][bj][m][n] = __builtin_amdgcn_mfma_f32_16x16x32_bf16(Bt[n][k], At[m][k], acc[ai][bj][m][n], 0, 0, 0); __builtin_amdgcn_s_setprio(0); } while (0)
; #define PG8_WAIT_V(n) asm volatile("s_waitcnt vmcnt(" #n ")" ::: "memory")
; #define PG8_WAIT_L(n) asm volatile("s_waitcnt lgkmcnt(" #n ")" ::: "memory")
; #define PG8_BAR __builtin_amdgcn_s_barrier()
; template <class Epi, class Sched, bool ALIGN_EPI = false, bool SP2 = false>
; __device__ __forceinline__ void gemm_phase(PG8_LAS unsigned char* lds, const Gemm g, const Sched& S, const Epi& E) {
;     ...
;         for (int t = 0; t < nt; t += 2) {
;             const bool last = (t == nt - 2);
;             const char* a1 = cA + (size_t)(t + 1) * kstep;
;             const char* a2 = last ? nA : cA + (size_t)(t + 2) * kstep; const char* b2 = last ? nB : cB + (size_t)(t + 2) * kstep;
;             const char* a3 = a2 + kstep; const char* b3 = b2 + kstep;
;     ...
;             PG8_LDB(B0, 1, 0); PG8_LDB(B1, 1, 1); PG8_SCHED; PG8_LDA(At, 1, 0); PG8_STAGE(PG8_SA(0, 1), a2 + hstep, voffA);
;             PG8_WAIT_V(8); PG8_WAIT_L(0); PG8_BAR; PG8_MMA(0, 0, At, B0); PG8_MMA(0, 1, At, B1); PG8_BAR; PG8_SCHED;
;             PG8_LDA(At, 1, 1); PG8_STAGE(PG8_SB(1, 0), b3, voffB); PG8_STAGE(PG8_SB(1, 1), b3 + hstep, voffB); PG8_STAGE(PG8_SA(1, 0), a3, voffA);
;             PG8_WAIT_V(8); PG8_WAIT_L(0); PG8_BAR; PG8_MMA(1, 0, At, B0); PG8_MMA(1, 1, At, B1); PG8_BAR; PG8_SCHED;
	ds_read_b128 v[146:149], v158
	ds_read_b128 v[150:153], v158 offset:1024
	ds_read_b128 v[164:167], v158 offset:2048
	ds_read_b128 v[168:171], v158 offset:3072
	ds_read_b128 v[172:175], v159
	ds_read_b128 v[176:179], v159 offset:1024
	ds_read_b128 v[180:183], v159 offset:2048
	ds_read_b128 v[184:187], v159 offset:3072
	s_add_u32 s66, s66, 0x80000
	s_addc_u32 s67, s67, 0
	s_mov_b32 m0, s13
	ds_read_b128 v[188:191], v157 offset:32768
	ds_read_b128 v[192:195], v157 offset:33792
	ds_read_b128 v[196:199], v157 offset:34816
	ds_read_b128 v[200:203], v157 offset:35840
	ds_read_b128 v[208:211], v157 offset:36864
	ds_read_b128 v[212:215], v157 offset:37888
	ds_read_b128 v[216:219], v157 offset:38912
	ds_read_b128 v[220:223], v157 offset:39936
	global_load_lds_dwordx4 v130, s[66:67]
	s_mov_b32 m0, s14
	s_nop 0
	global_load_lds_dwordx4 v134, s[66:67]
	s_waitcnt vmcnt(8)
	s_waitcnt lgkmcnt(0)
	s_barrier
	s_setprio 1
	s_waitcnt lgkmcnt(0)
	v_mfma_f32_16x16x32_bf16 v[126:129], v[146:149], v[188:191], v[126:129]
	v_mfma_f32_16x16x32_bf16 v[122:125], v[164:167], v[188:191], v[122:125]
	v_mfma_f32_16x16x32_bf16 v[110:113], v[146:149], v[196:199], v[110:113]
	v_mfma_f32_16x16x32_bf16 v[106:109], v[164:167], v[196:199], v[106:109]
	v_mfma_f32_16x16x32_bf16 v[94:97], v[146:149], v[208:211], v[94:97]
	v_mfma_f32_16x16x32_bf16 v[90:93], v[164:167], v[208:211], v[90:93]
	v_mfma_f32_16x16x32_bf16 v[78:81], v[146:149], v[216:219], v[78:81]
	v_mfma_f32_16x16x32_bf16 v[74:77], v[164:167], v[216:219], v[74:77]
	v_mfma_f32_16x16x32_bf16 v[126:129], v[150:153], v[192:195], v[126:129]
	v_mfma_f32_16x16x32_bf16 v[122:125], v[168:171], v[192:195], v[122:125]
	v_mfma_f32_16x16x32_bf16 v[110:113], v[150:153], v[200:203], v[110:113]
	v_mfma_f32_16x16x32_bf16 v[106:109], v[168:171], v[200:203], v[106:109]
	v_mfma_f32_16x16x32_bf16 v[94:97], v[150:153], v[212:215], v[94:97]
	v_mfma_f32_16x16x32_bf16 v[90:93], v[168:171], v[212:215], v[90:93]
	v_mfma_f32_16x16x32_bf16 v[78:81], v[150:153], v[220:223], v[78:81]
	v_mfma_f32_16x16x32_bf16 v[74:77], v[168:171], v[220:223], v[74:77]
	s_setprio 0
	s_setprio 1
	v_mfma_f32_16x16x32_bf16 v[118:121], v[172:175], v[188:191], v[118:121]
	v_mfma_f32_16x16x32_bf16 v[114:117], v[180:183], v[188:191], v[114:117]
	v_mfma_f32_16x16x32_bf16 v[102:105], v[172:175], v[196:199], v[102:105]
	v_mfma_f32_16x16x32_bf16 v[98:101], v[180:183], v[196:199], v[98:101]
	v_mfma_f32_16x16x32_bf16 v[86:89], v[172:175], v[208:211], v[86:89]
	v_mfma_f32_16x16x32_bf16 v[82:85], v[180:183], v[208:211], v[82:85]
	v_mfma_f32_16x16x32_bf16 v[70:73], v[172:175], v[216:219], v[70:73]
	v_mfma_f32_16x16x32_bf16 v[66:69], v[180:183], v[216:219], v[66:69]
	v_mfma_f32_16x16x32_bf16 v[118:121], v[176:179], v[192:195], v[118:121]
	v_mfma_f32_16x16x32_bf16 v[114:117], v[184:187], v[192:195], v[114:117]
	v_mfma_f32_16x16x32_bf16 v[102:105], v[176:179], v[200:203], v[102:105]
	v_mfma_f32_16x16x32_bf16 v[98:101], v[184:187], v[200:203], v[98:101]
	v_mfma_f32_16x16x32_bf16 v[86:89], v[176:179], v[212:215], v[86:89]
	v_mfma_f32_16x16x32_bf16 v[82:85], v[184:187], v[212:215], v[82:85]
	v_mfma_f32_16x16x32_bf16 v[70:73], v[176:179], v[220:223], v[70:73]
	v_mfma_f32_16x16x32_bf16 v[66:69], v[184:187], v[220:223], v[66:69]
	s_setprio 0
	s_barrier
	s_add_i32 s66, s57, s8
	s_nop 0
	s_mov_b32 m0, s66
	ds_read_b128 v[188:191], v157 offset:49152
	ds_read_b128 v[192:195], v157 offset:50176
	ds_read_b128 v[196:199], v157 offset:51200
	ds_read_b128 v[200:203], v157 offset:52224
	ds_read_b128 v[208:211], v157 offset:53248
	ds_read_b128 v[212:215], v157 offset:54272
	ds_read_b128 v[216:219], v157 offset:55296
	ds_read_b128 v[220:223], v157 offset:56320
	global_load_lds_dwordx4 v132, s[98:99]
	s_add_i32 m0, s66, 0x2000
	s_add_u32 s64, s64, 0x80080
	s_nop 0
	s_addc_u32 s65, s65, 0
	s_add_i32 s66, s58, s8
	global_load_lds_dwordx4 v136, s[98:99]
	s_mov_b32 m0, s66
	s_nop 0
	global_load_lds_dwordx4 v132, s[64:65]
	s_add_i32 m0, s66, 0x2000
	s_nop 0
	global_load_lds_dwordx4 v136, s[64:65]
	s_nop 0
	s_mov_b32 m0, s15
	s_nop 0
	global_load_lds_dwordx4 v130, s[100:101]
	s_nop 0
	s_mov_b32 m0, s16
	s_nop 0
	global_load_lds_dwordx4 v134, s[100:101]
	s_waitcnt vmcnt(8)
	s_waitcnt lgkmcnt(0)
	s_barrier
	s_setprio 1
	s_waitcnt lgkmcnt(0)
	v_mfma_f32_16x16x32_bf16 v[62:65], v[146:149], v[188:191], v[62:65]
	v_mfma_f32_16x16x32_bf16 v[58:61], v[164:167], v[188:191], v[58:61]
	v_mfma_f32_16x16x32_bf16 v[46:49], v[146:149], v[196:199], v[46:49]
	v_mfma_f32_16x16x32_bf16 v[42:45], v[164:167], v[196:199], v[42:45]
	v_mfma_f32_16x16x32_bf16 v[30:33], v[146:149], v[208:211], v[30:33]
	v_mfma_f32_16x16x32_bf16 v[26:29], v[164:167], v[208:211], v[26:29]
	v_mfma_f32_16x16x32_bf16 v[14:17], v[146:149], v[216:219], v[14:17]
	v_mfma_f32_16x16x32_bf16 v[10:13], v[164:167], v[216:219], v[10:13]
	v_mfma_f32_16x16x32_bf16 v[62:65], v[150:153], v[192:195], v[62:65]
	v_mfma_f32_16x16x32_bf16 v[58:61], v[168:171], v[192:195], v[58:61]
	v_mfma_f32_16x16x32_bf16 v[46:49], v[150:153], v[200:203], v[46:49]
	v_mfma_f32_16x16x32_bf16 v[42:45], v[168:171], v[200:203], v[42:45]
	v_mfma_f32_16x16x32_bf16 v[30:33], v[150:153], v[212:215], v[30:33]
	v_mfma_f32_16x16x32_bf16 v[26:29], v[168:171], v[212:215], v[26:29]
	v_mfma_f32_16x16x32_bf16 v[14:17], v[150:153], v[220:223], v[14:17]
	v_mfma_f32_16x16x32_bf16 v[10:13], v[168:171], v[220:223], v[10:13]
	s_setprio 0
	s_setprio 1
	v_mfma_f32_16x16x32_bf16 v[54:57], v[172:175], v[188:191], v[54:57]
	v_mfma_f32_16x16x32_bf16 v[50:53], v[180:183], v[188:191], v[50:53]
	v_mfma_f32_16x16x32_bf16 v[38:41], v[172:175], v[196:199], v[38:41]
	v_mfma_f32_16x16x32_bf16 v[34:37], v[180:183], v[196:199], v[34:37]
	v_mfma_f32_16x16x32_bf16 v[22:25], v[172:175], v[208:211], v[22:25]
	v_mfma_f32_16x16x32_bf16 v[18:21], v[180:183], v[208:211], v[18:21]
	v_mfma_f32_16x16x32_bf16 v[6:9], v[172:175], v[216:219], v[6:9]
	v_mfma_f32_16x16x32_bf16 v[2:5], v[180:183], v[216:219], v[2:5]
	v_mfma_f32_16x16x32_bf16 v[54:57], v[176:179], v[192:195], v[54:57]
	v_mfma_f32_16x16x32_bf16 v[50:53], v[184:187], v[192:195], v[50:53]
	v_mfma_f32_16x16x32_bf16 v[38:41], v[176:179], v[200:203], v[38:41]
	v_mfma_f32_16x16x32_bf16 v[34:37], v[184:187], v[200:203], v[34:37]
	v_mfma_f32_16x16x32_bf16 v[22:25], v[176:179], v[212:215], v[22:25]
	v_mfma_f32_16x16x32_bf16 v[18:21], v[184:187], v[212:215], v[18:21]
	v_mfma_f32_16x16x32_bf16 v[6:9], v[176:179], v[220:223], v[6:9]
	v_mfma_f32_16x16x32_bf16 v[2:5], v[184:187], v[220:223], v[2:5]
	s_setprio 0
	s_barrier
	s_add_i32 s69, s69, 2
	s_add_u32 s50, s50, 0x100
	s_addc_u32 s51, s51, 0
	s_add_u32 s63, s63, 0x100
	s_addc_u32 s68, s68, 0
	s_cmp_gt_u32 s69, 29
	s_cbranch_scc0 .LBB0_781
	s_and_b64 vcc, exec, s[36:37]
	s_cbranch_vccz .LBB0_784
	s_barrier

; #define PG8_STAGE(bufoff, gbase, voff) do { _Pragma("unroll") for (int _i = 0; _i < 2; ++_i) \
;         __builtin_amdgcn_global_load_lds((const unsigned*)((const char*)(gbase) + (voff)[_i]), (PG8_LAS unsigned*)(lds + (bufoff) + ldsw + _i * 8192), 16, 0, 0); } while (0)
; #define PG8_LDA(dst, b, h) do { _Pragma("unroll") for (int m = 0; m < 4; ++m) _Pragma("unroll") for (int k = 0; k < 2; ++k) dst[m][k] = *(const PG8_LAS bf16x8*)(lds + PG8_SA(b, h) + aoff + m * 2048 + k * 1024); } while (0)
; #define PG8_LDB(dst, b, h) do { _Pragma("unroll") for (int n = 0; n < 2; ++n) _Pragma("unroll") for (int k = 0; k < 2; ++k) dst[n][k] = *(const PG8_LAS bf16x8*)(lds + PG8_SB(b, h) + boff + n * 2048 + k * 1024); } while (0)
; #define PG8_MMA(ai, bj, At, Bt) do { __builtin_amdgcn_s_setprio(1); _Pragma("unroll") for (int m = 0; m < 4; ++m) _Pragma("unroll") for (int n = 0; n < 2; ++n) _Pragma("unroll") for (int k = 0; k < 2; ++k) \
;         acc[ai][bj][m][n] = __builtin_amdgcn_mfma_f32_16x16x32_bf16(Bt[n][k], At[m][k], acc[ai][bj][m][n], 0, 0, 0); __builtin_amdgcn_s_setprio(0); } while (0)
; #define PG8_WAIT_V(n) asm volatile("s_waitcnt vmcnt(" #n ")" ::: "memory")
; #define PG8_WAIT_L(n) asm volatile("s_waitcnt lgkmcnt(" #n ")" ::: "memory")
; #define PG8_BAR __builtin_amdgcn_s_barrier()
; #define PG8_SCHED __builtin_amdgcn_sched_barrier(0)
; template <class Epi, class Sched, bool ALIGN_EPI = false, bool SP2 = false>
; __device__ __forceinline__ void gemm_phase(PG8_LAS unsigned char* lds, const Gemm g, const Sched& S, const Epi& E) {
;     ...
;             PG8_LDB(B0, 0, 0); PG8_LDB(B1, 0, 1); PG8_SCHED; PG8_LDA(At, 0, 0); PG8_STAGE(PG8_SA(1, 1), a1 + hstep, voffA);
;             PG8_WAIT_V(8); PG8_WAIT_L(0); PG8_BAR; PG8_MMA(0, 0, At, B0); PG8_MMA(0, 1, At, B1); PG8_BAR; PG8_SCHED;
;             PG8_LDA(At, 0, 1); PG8_STAGE(PG8_SB(0, 0), b2, voffB); PG8_STAGE(PG8_SB(0, 1), b2 + hstep, voffB); PG8_STAGE(PG8_SA(0, 0), a2, voffA);
;             PG8_WAIT_V(8); PG8_WAIT_L(0); PG8_BAR; PG8_MMA(1, 0, At, B0); PG8_MMA(1, 1, At, B1); PG8_BAR; PG8_SCHED;
.LBB0_824:
	ds_read_b128 v[146:149], v151
	ds_read_b128 v[158:161], v151 offset:1024
	ds_read_b128 v[164:167], v151 offset:2048
	ds_read_b128 v[168:171], v151 offset:3072
	ds_read_b128 v[172:175], v152
	ds_read_b128 v[176:179], v152 offset:1024
	ds_read_b128 v[180:183], v152 offset:2048
	ds_read_b128 v[184:187], v152 offset:3072
	s_add_u32 s64, s50, 0xfff80080
	s_addc_u32 s65, s51, -1
	s_cmp_eq_u32 s69, 28
	s_cselect_b32 s67, s43, s65
	s_cselect_b32 s66, s49, s64
	s_cselect_b32 s65, s41, s68
	s_cselect_b32 s64, s62, s63
	s_add_i32 m0, s8, 0xc000
	ds_read_b128 v[188:191], v153
	ds_read_b128 v[192:195], v153 offset:1024
	ds_read_b128 v[196:199], v153 offset:2048
	ds_read_b128 v[200:203], v153 offset:3072
	ds_read_b128 v[208:211], v153 offset:4096
	ds_read_b128 v[212:215], v153 offset:5120
	ds_read_b128 v[216:219], v153 offset:6144
	ds_read_b128 v[220:223], v153 offset:7168
	global_load_lds_dwordx4 v138, s[50:51]
	s_add_i32 m0, s8, 0xe000
	s_nop 0
	global_load_lds_dwordx4 v140, s[50:51]
	s_waitcnt vmcnt(8)
	s_waitcnt lgkmcnt(0)
	s_barrier
	s_setprio 1
	s_waitcnt lgkmcnt(0)
	v_mfma_f32_16x16x32_bf16 v[126:129], v[146:149], v[188:191], v[126:129]
	v_mfma_f32_16x16x32_bf16 v[122:125], v[164:167], v[188:191], v[122:125]
	v_mfma_f32_16x16x32_bf16 v[110:113], v[146:149], v[196:199], v[110:113]
	v_mfma_f32_16x16x32_bf16 v[106:109], v[164:167], v[196:199], v[106:109]
	v_mfma_f32_16x16x32_bf16 v[94:97], v[146:149], v[208:211], v[94:97]
	v_mfma_f32_16x16x32_bf16 v[90:93], v[164:167], v[208:211], v[90:93]
	v_mfma_f32_16x16x32_bf16 v[78:81], v[146:149], v[216:219], v[78:81]
	v_mfma_f32_16x16x32_bf16 v[74:77], v[164:167], v[216:219], v[74:77]
	v_mfma_f32_16x16x32_bf16 v[126:129], v[158:161], v[192:195], v[126:129]
	v_mfma_f32_16x16x32_bf16 v[122:125], v[168:171], v[192:195], v[122:125]
	v_mfma_f32_16x16x32_bf16 v[110:113], v[158:161], v[200:203], v[110:113]
	v_mfma_f32_16x16x32_bf16 v[106:109], v[168:171], v[200:203], v[106:109]
	v_mfma_f32_16x16x32_bf16 v[94:97], v[158:161], v[212:215], v[94:97]
	v_mfma_f32_16x16x32_bf16 v[90:93], v[168:171], v[212:215], v[90:93]
	v_mfma_f32_16x16x32_bf16 v[78:81], v[158:161], v[220:223], v[78:81]
	v_mfma_f32_16x16x32_bf16 v[74:77], v[168:171], v[220:223], v[74:77]
	s_setprio 0
	s_setprio 1
	v_mfma_f32_16x16x32_bf16 v[118:121], v[172:175], v[188:191], v[118:121]
	v_mfma_f32_16x16x32_bf16 v[114:117], v[180:183], v[188:191], v[114:117]
	v_mfma_f32_16x16x32_bf16 v[102:105], v[172:175], v[196:199], v[102:105]
	v_mfma_f32_16x16x32_bf16 v[98:101], v[180:183], v[196:199], v[98:101]
	v_mfma_f32_16x16x32_bf16 v[86:89], v[172:175], v[208:211], v[86:89]
	v_mfma_f32_16x16x32_bf16 v[82:85], v[180:183], v[208:211], v[82:85]
	v_mfma_f32_16x16x32_bf16 v[70:73], v[172:175], v[216:219], v[70:73]
	v_mfma_f32_16x16x32_bf16 v[66:69], v[180:183], v[216:219], v[66:69]
	v_mfma_f32_16x16x32_bf16 v[118:121], v[176:179], v[192:195], v[118:121]
	v_mfma_f32_16x16x32_bf16 v[114:117], v[184:187], v[192:195], v[114:117]
	v_mfma_f32_16x16x32_bf16 v[102:105], v[176:179], v[200:203], v[102:105]
	v_mfma_f32_16x16x32_bf16 v[98:101], v[184:187], v[200:203], v[98:101]
	v_mfma_f32_16x16x32_bf16 v[86:89], v[176:179], v[212:215], v[86:89]
	v_mfma_f32_16x16x32_bf16 v[82:85], v[184:187], v[212:215], v[82:85]
	v_mfma_f32_16x16x32_bf16 v[70:73], v[176:179], v[220:223], v[70:73]
	v_mfma_f32_16x16x32_bf16 v[66:69], v[184:187], v[220:223], v[66:69]
	s_setprio 0
	s_barrier
	s_add_u32 s98, s64, s20
	s_addc_u32 s99, s65, s21
	s_add_u32 s100, s66, s20
	s_addc_u32 s101, s67, s21
	s_add_i32 s70, s35, s2
	s_nop 0
	s_mov_b32 m0, s70
	ds_read_b128 v[188:191], v153 offset:16384
	ds_read_b128 v[192:195], v153 offset:17408
	ds_read_b128 v[196:199], v153 offset:18432
	ds_read_b128 v[200:203], v153 offset:19456
	ds_read_b128 v[208:211], v153 offset:20480
	ds_read_b128 v[212:215], v153 offset:21504
	ds_read_b128 v[216:219], v153 offset:22528
	ds_read_b128 v[220:223], v153 offset:23552
	global_load_lds_dwordx4 v132, s[64:65]
	s_add_i32 m0, s70, 0x2000
	s_add_u32 s70, s64, 0x80000
	s_nop 0
	s_addc_u32 s71, s65, 0
	s_add_i32 s72, s57, s2
	global_load_lds_dwordx4 v136, s[64:65]
	s_mov_b32 m0, s72
	s_nop 0
	global_load_lds_dwordx4 v132, s[70:71]
	s_add_i32 m0, s72, 0x2000
	s_nop 0
	global_load_lds_dwordx4 v136, s[70:71]
	s_nop 0
	s_mov_b32 m0, s8
	s_nop 0
	global_load_lds_dwordx4 v130, s[66:67]
	s_mov_b32 m0, s9
	s_nop 0
	global_load_lds_dwordx4 v134, s[66:67]
	s_waitcnt vmcnt(8)
	s_waitcnt lgkmcnt(0)
	s_barrier
	s_setprio 1
	s_waitcnt lgkmcnt(0)
	v_mfma_f32_16x16x32_bf16 v[62:65], v[146:149], v[188:191], v[62:65]
	v_mfma_f32_16x16x32_bf16 v[58:61], v[164:167], v[188:191], v[58:61]
	v_mfma_f32_16x16x32_bf16 v[46:49], v[146:149], v[196:199], v[46:49]
	v_mfma_f32_16x16x32_bf16 v[42:45], v[164:167], v[196:199], v[42:45]
	v_mfma_f32_16x16x32_bf16 v[30:33], v[146:149], v[208:211], v[30:33]
	v_mfma_f32_16x16x32_bf16 v[26:29], v[164:167], v[208:211], v[26:29]
	v_mfma_f32_16x16x32_bf16 v[14:17], v[146:149], v[216:219], v[14:17]
	v_mfma_f32_16x16x32_bf16 v[10:13], v[164:167], v[216:219], v[10:13]
	v_mfma_f32_16x16x32_bf16 v[62:65], v[158:161], v[192:195], v[62:65]
	v_mfma_f32_16x16x32_bf16 v[58:61], v[168:171], v[192:195], v[58:61]
	v_mfma_f32_16x16x32_bf16 v[46:49], v[158:161], v[200:203], v[46:49]
	v_mfma_f32_16x16x32_bf16 v[42:45], v[168:171], v[200:203], v[42:45]
	v_mfma_f32_16x16x32_bf16 v[30:33], v[158:161], v[212:215], v[30:33]
	v_mfma_f32_16x16x32_bf16 v[26:29], v[168:171], v[212:215], v[26:29]
	v_mfma_f32_16x16x32_bf16 v[14:17], v[158:161], v[220:223], v[14:17]
	v_mfma_f32_16x16x32_bf16 v[10:13], v[168:171], v[220:223], v[10:13]
	s_setprio 0
	s_setprio 1
	v_mfma_f32_16x16x32_bf16 v[54:57], v[172:175], v[188:191], v[54:57]
	v_mfma_f32_16x16x32_bf16 v[50:53], v[180:183], v[188:191], v[50:53]
	v_mfma_f32_16x16x32_bf16 v[38:41], v[172:175], v[196:199], v[38:41]
	v_mfma_f32_16x16x32_bf16 v[34:37], v[180:183], v[196:199], v[34:37]
	v_mfma_f32_16x16x32_bf16 v[22:25], v[172:175], v[208:211], v[22:25]
	v_mfma_f32_16x16x32_bf16 v[18:21], v[180:183], v[208:211], v[18:21]
	v_mfma_f32_16x16x32_bf16 v[6:9], v[172:175], v[216:219], v[6:9]
	v_mfma_f32_16x16x32_bf16 v[2:5], v[180:183], v[216:219], v[2:5]
	v_mfma_f32_16x16x32_bf16 v[54:57], v[176:179], v[192:195], v[54:57]
	v_mfma_f32_16x16x32_bf16 v[50:53], v[184:187], v[192:195], v[50:53]
	v_mfma_f32_16x16x32_bf16 v[38:41], v[176:179], v[200:203], v[38:41]
	v_mfma_f32_16x16x32_bf16 v[34:37], v[184:187], v[200:203], v[34:37]
	v_mfma_f32_16x16x32_bf16 v[22:25], v[176:179], v[212:215], v[22:25]
	v_mfma_f32_16x16x32_bf16 v[18:21], v[184:187], v[212:215], v[18:21]
	v_mfma_f32_16x16x32_bf16 v[6:9], v[176:179], v[220:223], v[6:9]
	v_mfma_f32_16x16x32_bf16 v[2:5], v[184:187], v[220:223], v[2:5]
	s_setprio 0
	s_barrier
; #define PG8_STAGE(bufoff, gbase, voff) do { _Pragma("unroll") for (int _i = 0; _i < 2; ++_i) \
;         __builtin_amdgcn_global_load_lds((const unsigned*)((const char*)(gbase) + (voff)[_i]), (PG8_LAS unsigned*)(lds + (bufoff) + ldsw + _i * 8192), 16, 0, 0); } while (0)
; #define PG8_LDA(dst, b, h) do { _Pragma("unroll") for (int m = 0; m < 4; ++m) _Pragma("unroll") for (int k = 0; k < 2; ++k) dst[m][k] = *(const PG8_LAS bf16x8*)(lds + PG8_SA(b, h) + aoff + m * 2048 + k * 1024); } while (0)
; #define PG8_LDB(dst, b, h) do { _Pragma("unroll") for (int n = 0; n < 2; ++n) _Pragma("unroll") for (int k = 0; k < 2; ++k) dst[n][k] = *(const PG8_LAS bf16x8*)(lds + PG8_SB(b, h) + boff + n * 2048 + k * 1024); } while (0)
; #define PG8_MMA(ai, bj, At, Bt) do { __builtin_amdgcn_s_setprio(1); _Pragma("unroll") for (int m = 0; m < 4; ++m) _Pragma("unroll") for (int n = 0; n < 2; ++n) _Pragma("unroll") for (int k = 0; k < 2; ++k) \
;         acc[ai][bj][m][n] = __builtin_amdgcn_mfma_f32_16x16x32_bf16(Bt[n][k], At[m][k], acc[ai][bj][m][n], 0, 0, 0); __builtin_amdgcn_s_setprio(0); } while (0)
; #define PG8_WAIT_V(n) asm volatile("s_waitcnt vmcnt(" #n ")" ::: "memory")
; #define PG8_WAIT_L(n) asm volatile("s_waitcnt lgkmcnt(" #n ")" ::: "memory")
; #define PG8_BAR __builtin_amdgcn_s_barrier()
; template <class Epi, class Sched, bool ALIGN_EPI = false, bool SP2 = false>
; __device__ __forceinline__ void gemm_phase(PG8_LAS unsigned char* lds, const Gemm g, const Sched& S, const Epi& E) {
;     ...
;         for (int t = 0; t < nt; t += 2) {
;             const bool last = (t == nt - 2);
;             const char* a1 = cA + (size_t)(t + 1) * kstep;
;             const char* a2 = last ? nA : cA + (size_t)(t + 2) * kstep; const char* b2 = last ? nB : cB + (size_t)(t + 2) * kstep;
;             const char* a3 = a2 + kstep; const char* b3 = b2 + kstep;
;     ...
;             PG8_LDB(B0, 1, 0); PG8_LDB(B1, 1, 1); PG8_SCHED; PG8_LDA(At, 1, 0); PG8_STAGE(PG8_SA(0, 1), a2 + hstep, voffA);
;             PG8_WAIT_V(8); PG8_WAIT_L(0); PG8_BAR; PG8_MMA(0, 0, At, B0); PG8_MMA(0, 1, At, B1); PG8_BAR; PG8_SCHED;
;             PG8_LDA(At, 1, 1); PG8_STAGE(PG8_SB(1, 0), b3, voffB); PG8_STAGE(PG8_SB(1, 1), b3 + hstep, voffB); PG8_STAGE(PG8_SA(1, 0), a3, voffA);
;             PG8_WAIT_V(8); PG8_WAIT_L(0); PG8_BAR; PG8_MMA(1, 0, At, B0); PG8_MMA(1, 1, At, B1); PG8_BAR; PG8_SCHED;
	ds_read_b128 v[146:149], v154
	ds_read_b128 v[158:161], v154 offset:1024
	ds_read_b128 v[164:167], v154 offset:2048
	ds_read_b128 v[168:171], v154 offset:3072
	ds_read_b128 v[172:175], v155
	ds_read_b128 v[176:179], v155 offset:1024
	ds_read_b128 v[180:183], v155 offset:2048
	ds_read_b128 v[184:187], v155 offset:3072
	s_add_u32 s66, s66, 0x80000
	s_addc_u32 s67, s67, 0
	s_mov_b32 m0, s12
	ds_read_b128 v[188:191], v153 offset:32768
	ds_read_b128 v[192:195], v153 offset:33792
	ds_read_b128 v[196:199], v153 offset:34816
	ds_read_b128 v[200:203], v153 offset:35840
	ds_read_b128 v[208:211], v153 offset:36864
	ds_read_b128 v[212:215], v153 offset:37888
	ds_read_b128 v[216:219], v153 offset:38912
	ds_read_b128 v[220:223], v153 offset:39936
	global_load_lds_dwordx4 v130, s[66:67]
	s_mov_b32 m0, s13
	s_nop 0
	global_load_lds_dwordx4 v134, s[66:67]
	s_waitcnt vmcnt(8)
	s_waitcnt lgkmcnt(0)
	s_barrier
	s_setprio 1
	s_waitcnt lgkmcnt(0)
	v_mfma_f32_16x16x32_bf16 v[126:129], v[146:149], v[188:191], v[126:129]
	v_mfma_f32_16x16x32_bf16 v[122:125], v[164:167], v[188:191], v[122:125]
	v_mfma_f32_16x16x32_bf16 v[110:113], v[146:149], v[196:199], v[110:113]
	v_mfma_f32_16x16x32_bf16 v[106:109], v[164:167], v[196:199], v[106:109]
	v_mfma_f32_16x16x32_bf16 v[94:97], v[146:149], v[208:211], v[94:97]
	v_mfma_f32_16x16x32_bf16 v[90:93], v[164:167], v[208:211], v[90:93]
	v_mfma_f32_16x16x32_bf16 v[78:81], v[146:149], v[216:219], v[78:81]
	v_mfma_f32_16x16x32_bf16 v[74:77], v[164:167], v[216:219], v[74:77]
	v_mfma_f32_16x16x32_bf16 v[126:129], v[158:161], v[192:195], v[126:129]
	v_mfma_f32_16x16x32_bf16 v[122:125], v[168:171], v[192:195], v[122:125]
	v_mfma_f32_16x16x32_bf16 v[110:113], v[158:161], v[200:203], v[110:113]
	v_mfma_f32_16x16x32_bf16 v[106:109], v[168:171], v[200:203], v[106:109]
	v_mfma_f32_16x16x32_bf16 v[94:97], v[158:161], v[212:215], v[94:97]
	v_mfma_f32_16x16x32_bf16 v[90:93], v[168:171], v[212:215], v[90:93]
	v_mfma_f32_16x16x32_bf16 v[78:81], v[158:161], v[220:223], v[78:81]
	v_mfma_f32_16x16x32_bf16 v[74:77], v[168:171], v[220:223], v[74:77]
	s_setprio 0
	s_setprio 1
	v_mfma_f32_16x16x32_bf16 v[118:121], v[172:175], v[188:191], v[118:121]
	v_mfma_f32_16x16x32_bf16 v[114:117], v[180:183], v[188:191], v[114:117]
	v_mfma_f32_16x16x32_bf16 v[102:105], v[172:175], v[196:199], v[102:105]
	v_mfma_f32_16x16x32_bf16 v[98:101], v[180:183], v[196:199], v[98:101]
	v_mfma_f32_16x16x32_bf16 v[86:89], v[172:175], v[208:211], v[86:89]
	v_mfma_f32_16x16x32_bf16 v[82:85], v[180:183], v[208:211], v[82:85]
	v_mfma_f32_16x16x32_bf16 v[70:73], v[172:175], v[216:219], v[70:73]
	v_mfma_f32_16x16x32_bf16 v[66:69], v[180:183], v[216:219], v[66:69]
	v_mfma_f32_16x16x32_bf16 v[118:121], v[176:179], v[192:195], v[118:121]
	v_mfma_f32_16x16x32_bf16 v[114:117], v[184:187], v[192:195], v[114:117]
	v_mfma_f32_16x16x32_bf16 v[102:105], v[176:179], v[200:203], v[102:105]
	v_mfma_f32_16x16x32_bf16 v[98:101], v[184:187], v[200:203], v[98:101]
	v_mfma_f32_16x16x32_bf16 v[86:89], v[176:179], v[212:215], v[86:89]
	v_mfma_f32_16x16x32_bf16 v[82:85], v[184:187], v[212:215], v[82:85]
	v_mfma_f32_16x16x32_bf16 v[70:73], v[176:179], v[220:223], v[70:73]
	v_mfma_f32_16x16x32_bf16 v[66:69], v[184:187], v[220:223], v[66:69]
	s_setprio 0
	s_barrier
	s_add_i32 s66, s58, s2
	s_nop 0
	s_mov_b32 m0, s66
	ds_read_b128 v[188:191], v153 offset:49152
	ds_read_b128 v[192:195], v153 offset:50176
	ds_read_b128 v[196:199], v153 offset:51200
	ds_read_b128 v[200:203], v153 offset:52224
	ds_read_b128 v[208:211], v153 offset:53248
	ds_read_b128 v[212:215], v153 offset:54272
	ds_read_b128 v[216:219], v153 offset:55296
	ds_read_b128 v[220:223], v153 offset:56320
	global_load_lds_dwordx4 v132, s[98:99]
	s_add_i32 m0, s66, 0x2000
	s_add_u32 s64, s64, 0x80080
	s_nop 0
	s_addc_u32 s65, s65, 0
	s_add_i32 s66, s59, s2
	global_load_lds_dwordx4 v136, s[98:99]
	s_mov_b32 m0, s66
	s_nop 0
	global_load_lds_dwordx4 v132, s[64:65]
	s_add_i32 m0, s66, 0x2000
	s_nop 0
	global_load_lds_dwordx4 v136, s[64:65]
	s_nop 0
	s_mov_b32 m0, s14
	s_nop 0
	global_load_lds_dwordx4 v130, s[100:101]
	s_nop 0
	s_mov_b32 m0, s15
	s_nop 0
	global_load_lds_dwordx4 v134, s[100:101]
	s_waitcnt vmcnt(8)
	s_waitcnt lgkmcnt(0)
	s_barrier
	s_setprio 1
	s_waitcnt lgkmcnt(0)
	v_mfma_f32_16x16x32_bf16 v[62:65], v[146:149], v[188:191], v[62:65]
	v_mfma_f32_16x16x32_bf16 v[58:61], v[164:167], v[188:191], v[58:61]
	v_mfma_f32_16x16x32_bf16 v[46:49], v[146:149], v[196:199], v[46:49]
	v_mfma_f32_16x16x32_bf16 v[42:45], v[164:167], v[196:199], v[42:45]
	v_mfma_f32_16x16x32_bf16 v[30:33], v[146:149], v[208:211], v[30:33]
	v_mfma_f32_16x16x32_bf16 v[26:29], v[164:167], v[208:211], v[26:29]
	v_mfma_f32_16x16x32_bf16 v[14:17], v[146:149], v[216:219], v[14:17]
	v_mfma_f32_16x16x32_bf16 v[10:13], v[164:167], v[216:219], v[10:13]
	v_mfma_f32_16x16x32_bf16 v[62:65], v[158:161], v[192:195], v[62:65]
	v_mfma_f32_16x16x32_bf16 v[58:61], v[168:171], v[192:195], v[58:61]
	v_mfma_f32_16x16x32_bf16 v[46:49], v[158:161], v[200:203], v[46:49]
	v_mfma_f32_16x16x32_bf16 v[42:45], v[168:171], v[200:203], v[42:45]
	v_mfma_f32_16x16x32_bf16 v[30:33], v[158:161], v[212:215], v[30:33]
	v_mfma_f32_16x16x32_bf16 v[26:29], v[168:171], v[212:215], v[26:29]
	v_mfma_f32_16x16x32_bf16 v[14:17], v[158:161], v[220:223], v[14:17]
	v_mfma_f32_16x16x32_bf16 v[10:13], v[168:171], v[220:223], v[10:13]
	s_setprio 0
	s_setprio 1
	v_mfma_f32_16x16x32_bf16 v[54:57], v[172:175], v[188:191], v[54:57]
	v_mfma_f32_16x16x32_bf16 v[50:53], v[180:183], v[188:191], v[50:53]
	v_mfma_f32_16x16x32_bf16 v[38:41], v[172:175], v[196:199], v[38:41]
	v_mfma_f32_16x16x32_bf16 v[34:37], v[180:183], v[196:199], v[34:37]
	v_mfma_f32_16x16x32_bf16 v[22:25], v[172:175], v[208:211], v[22:25]
	v_mfma_f32_16x16x32_bf16 v[18:21], v[180:183], v[208:211], v[18:21]
	v_mfma_f32_16x16x32_bf16 v[6:9], v[172:175], v[216:219], v[6:9]
	v_mfma_f32_16x16x32_bf16 v[2:5], v[180:183], v[216:219], v[2:5]
	v_mfma_f32_16x16x32_bf16 v[54:57], v[176:179], v[192:195], v[54:57]
	v_mfma_f32_16x16x32_bf16 v[50:53], v[184:187], v[192:195], v[50:53]
	v_mfma_f32_16x16x32_bf16 v[38:41], v[176:179], v[200:203], v[38:41]
	v_mfma_f32_16x16x32_bf16 v[34:37], v[184:187], v[200:203], v[34:37]
	v_mfma_f32_16x16x32_bf16 v[22:25], v[176:179], v[212:215], v[22:25]
	v_mfma_f32_16x16x32_bf16 v[18:21], v[184:187], v[212:215], v[18:21]
	v_mfma_f32_16x16x32_bf16 v[6:9], v[176:179], v[220:223], v[6:9]
	v_mfma_f32_16x16x32_bf16 v[2:5], v[184:187], v[220:223], v[2:5]
	s_setprio 0
	s_barrier
	s_add_i32 s69, s69, 2
	s_add_u32 s50, s50, 0x100
	s_addc_u32 s51, s51, 0
	s_add_u32 s63, s63, 0x100
	s_addc_u32 s68, s68, 0
	s_cmp_gt_u32 s69, 29
	s_cbranch_scc0 .LBB0_824
	s_and_b64 vcc, exec, s[38:39]
	s_cbranch_vccz .LBB0_827
	s_barrier

; #define PG8_STAGE(bufoff, gbase, voff) do { _Pragma("unroll") for (int _i = 0; _i < 2; ++_i) \
;         __builtin_amdgcn_global_load_lds((const unsigned*)((const char*)(gbase) + (voff)[_i]), (PG8_LAS unsigned*)(lds + (bufoff) + ldsw + _i * 8192), 16, 0, 0); } while (0)
; #define PG8_LDA(dst, b, h) do { _Pragma("unroll") for (int m = 0; m < 4; ++m) _Pragma("unroll") for (int k = 0; k < 2; ++k) dst[m][k] = *(const PG8_LAS bf16x8*)(lds + PG8_SA(b, h) + aoff + m * 2048 + k * 1024); } while (0)
; #define PG8_LDB(dst, b, h) do { _Pragma("unroll") for (int n = 0; n < 2; ++n) _Pragma("unroll") for (int k = 0; k < 2; ++k) dst[n][k] = *(const PG8_LAS bf16x8*)(lds + PG8_SB(b, h) + boff + n * 2048 + k * 1024); } while (0)
; #define PG8_MMA(ai, bj, At, Bt) do { __builtin_amdgcn_s_setprio(1); _Pragma("unroll") for (int m = 0; m < 4; ++m) _Pragma("unroll") for (int n = 0; n < 2; ++n) _Pragma("unroll") for (int k = 0; k < 2; ++k) \
;         acc[ai][bj][m][n] = __builtin_amdgcn_mfma_f32_16x16x32_bf16(Bt[n][k], At[m][k], acc[ai][bj][m][n], 0, 0, 0); __builtin_amdgcn_s_setprio(0); } while (0)
; #define PG8_WAIT_V(n) asm volatile("s_waitcnt vmcnt(" #n ")" ::: "memory")
; #define PG8_WAIT_L(n) asm volatile("s_waitcnt lgkmcnt(" #n ")" ::: "memory")
; #define PG8_BAR __builtin_amdgcn_s_barrier()
; #define PG8_SCHED __builtin_amdgcn_sched_barrier(0)
; template <class Epi, class Sched, bool ALIGN_EPI = false, bool SP2 = false>
; __device__ __forceinline__ void gemm_phase(PG8_LAS unsigned char* lds, const Gemm g, const Sched& S, const Epi& E) {
;     ...
;             PG8_LDB(B0, 0, 0); PG8_LDB(B1, 0, 1); PG8_SCHED; PG8_LDA(At, 0, 0); PG8_STAGE(PG8_SA(1, 1), a1 + hstep, voffA);
;             PG8_WAIT_V(8); PG8_WAIT_L(0); PG8_BAR; PG8_MMA(0, 0, At, B0); PG8_MMA(0, 1, At, B1); PG8_BAR; PG8_SCHED;
;             PG8_LDA(At, 0, 1); PG8_STAGE(PG8_SB(0, 0), b2, voffB); PG8_STAGE(PG8_SB(0, 1), b2 + hstep, voffB); PG8_STAGE(PG8_SA(0, 0), a2, voffA);
;             PG8_WAIT_V(8); PG8_WAIT_L(0); PG8_BAR; PG8_MMA(1, 0, At, B0); PG8_MMA(1, 1, At, B1); PG8_BAR; PG8_SCHED;
.LBB0_908:
	ds_read_b128 v[82:85], v207
	ds_read_b128 v[86:89], v207 offset:1024
	ds_read_b128 v[90:93], v207 offset:2048
	ds_read_b128 v[94:97], v207 offset:3072
	ds_read_b128 v[98:101], v208
	ds_read_b128 v[102:105], v208 offset:1024
	ds_read_b128 v[106:109], v208 offset:2048
	ds_read_b128 v[110:113], v208 offset:3072
	s_add_u32 s70, s68, 0xfff80080
	s_addc_u32 s71, s69, -1
	s_cmp_eq_u32 s86, 28
	s_cselect_b32 s73, s49, s71
	s_cselect_b32 s72, s82, s70
	s_cselect_b32 s71, s47, s85
	s_cselect_b32 s70, s83, s84
	s_add_i32 m0, s35, 0xc000
	ds_read_b128 v[186:189], v209
	ds_read_b128 v[190:193], v209 offset:1024
	ds_read_b128 v[194:197], v209 offset:2048
	ds_read_b128 v[198:201], v209 offset:3072
	ds_read_b128 v[202:205], v209 offset:4096
	ds_read_b128 v[216:219], v209 offset:5120
	ds_read_b128 v[220:223], v209 offset:6144
	ds_read_b128 v[224:227], v209 offset:7168
	global_load_lds_dwordx4 v178, s[68:69]
	s_add_i32 m0, s35, 0xe000
	s_nop 0
	global_load_lds_dwordx4 v180, s[68:69]
	s_waitcnt vmcnt(8)
	s_waitcnt lgkmcnt(0)
	s_barrier
	s_setprio 1
	s_waitcnt lgkmcnt(0)
	v_mfma_f32_16x16x32_bf16 v[158:161], v[82:85], v[186:189], v[158:161]
	v_mfma_f32_16x16x32_bf16 v[154:157], v[90:93], v[186:189], v[154:157]
	v_mfma_f32_16x16x32_bf16 v[142:145], v[82:85], v[194:197], v[142:145]
	v_mfma_f32_16x16x32_bf16 v[138:141], v[90:93], v[194:197], v[138:141]
	v_mfma_f32_16x16x32_bf16 v[126:129], v[82:85], v[202:205], v[126:129]
	v_mfma_f32_16x16x32_bf16 v[122:125], v[90:93], v[202:205], v[122:125]
	v_mfma_f32_16x16x32_bf16 v[78:81], v[82:85], v[220:223], v[78:81]
	v_mfma_f32_16x16x32_bf16 v[70:73], v[90:93], v[220:223], v[70:73]
	v_mfma_f32_16x16x32_bf16 v[158:161], v[86:89], v[190:193], v[158:161]
	v_mfma_f32_16x16x32_bf16 v[154:157], v[94:97], v[190:193], v[154:157]
	v_mfma_f32_16x16x32_bf16 v[142:145], v[86:89], v[198:201], v[142:145]
	v_mfma_f32_16x16x32_bf16 v[138:141], v[94:97], v[198:201], v[138:141]
	v_mfma_f32_16x16x32_bf16 v[126:129], v[86:89], v[216:219], v[126:129]
	v_mfma_f32_16x16x32_bf16 v[122:125], v[94:97], v[216:219], v[122:125]
	v_mfma_f32_16x16x32_bf16 v[78:81], v[86:89], v[224:227], v[78:81]
	v_mfma_f32_16x16x32_bf16 v[70:73], v[94:97], v[224:227], v[70:73]
	s_setprio 0
	s_setprio 1
	v_mfma_f32_16x16x32_bf16 v[150:153], v[98:101], v[186:189], v[150:153]
	v_mfma_f32_16x16x32_bf16 v[146:149], v[106:109], v[186:189], v[146:149]
	v_mfma_f32_16x16x32_bf16 v[134:137], v[98:101], v[194:197], v[134:137]
	v_mfma_f32_16x16x32_bf16 v[130:133], v[106:109], v[194:197], v[130:133]
	v_mfma_f32_16x16x32_bf16 v[118:121], v[98:101], v[202:205], v[118:121]
	v_mfma_f32_16x16x32_bf16 v[114:117], v[106:109], v[202:205], v[114:117]
	v_mfma_f32_16x16x32_bf16 v[74:77], v[98:101], v[220:223], v[74:77]
	v_mfma_f32_16x16x32_bf16 v[66:69], v[106:109], v[220:223], v[66:69]
	v_mfma_f32_16x16x32_bf16 v[150:153], v[102:105], v[190:193], v[150:153]
	v_mfma_f32_16x16x32_bf16 v[146:149], v[110:113], v[190:193], v[146:149]
	v_mfma_f32_16x16x32_bf16 v[134:137], v[102:105], v[198:201], v[134:137]
	v_mfma_f32_16x16x32_bf16 v[130:133], v[110:113], v[198:201], v[130:133]
	v_mfma_f32_16x16x32_bf16 v[118:121], v[102:105], v[216:219], v[118:121]
	v_mfma_f32_16x16x32_bf16 v[114:117], v[110:113], v[216:219], v[114:117]
	v_mfma_f32_16x16x32_bf16 v[74:77], v[102:105], v[224:227], v[74:77]
	v_mfma_f32_16x16x32_bf16 v[66:69], v[110:113], v[224:227], v[66:69]
	s_setprio 0
	s_barrier
	s_add_u32 s98, s70, s28
	s_addc_u32 s99, s71, s29
	s_add_u32 s100, s72, s28
	s_addc_u32 s101, s73, s29
	s_add_i32 s87, s75, s16
	s_nop 0
	s_mov_b32 m0, s87
	ds_read_b128 v[186:189], v209 offset:16384
	ds_read_b128 v[190:193], v209 offset:17408
	ds_read_b128 v[194:197], v209 offset:18432
	ds_read_b128 v[198:201], v209 offset:19456
	ds_read_b128 v[202:205], v209 offset:20480
	ds_read_b128 v[216:219], v209 offset:21504
	ds_read_b128 v[220:223], v209 offset:22528
	ds_read_b128 v[224:227], v209 offset:23552
	global_load_lds_dwordx4 v170, s[70:71]
	s_add_i32 m0, s87, 0x2000
	s_add_u32 s88, s70, 0x80000
	s_nop 0
	s_addc_u32 s89, s71, 0
	s_add_i32 s87, s76, s16
	global_load_lds_dwordx4 v166, s[70:71]
	s_mov_b32 m0, s87
	s_nop 0
	global_load_lds_dwordx4 v170, s[88:89]
	s_add_i32 m0, s87, 0x2000
	s_nop 0
	global_load_lds_dwordx4 v166, s[88:89]
	s_nop 0
	s_mov_b32 m0, s35
	s_nop 0
	global_load_lds_dwordx4 v172, s[72:73]
	s_mov_b32 m0, s57
	s_nop 0
	global_load_lds_dwordx4 v168, s[72:73]
	s_waitcnt vmcnt(8)
	s_waitcnt lgkmcnt(0)
	s_barrier
	s_setprio 1
	s_waitcnt lgkmcnt(0)
	v_mfma_f32_16x16x32_bf16 v[62:65], v[82:85], v[186:189], v[62:65]
	v_mfma_f32_16x16x32_bf16 v[58:61], v[90:93], v[186:189], v[58:61]
	v_mfma_f32_16x16x32_bf16 v[46:49], v[82:85], v[194:197], v[46:49]
	v_mfma_f32_16x16x32_bf16 v[42:45], v[90:93], v[194:197], v[42:45]
	v_mfma_f32_16x16x32_bf16 v[30:33], v[82:85], v[202:205], v[30:33]
	v_mfma_f32_16x16x32_bf16 v[26:29], v[90:93], v[202:205], v[26:29]
	v_mfma_f32_16x16x32_bf16 v[10:13], v[82:85], v[220:223], v[10:13]
	v_mfma_f32_16x16x32_bf16 v[6:9], v[90:93], v[220:223], v[6:9]
	v_mfma_f32_16x16x32_bf16 v[62:65], v[86:89], v[190:193], v[62:65]
	v_mfma_f32_16x16x32_bf16 v[58:61], v[94:97], v[190:193], v[58:61]
	v_mfma_f32_16x16x32_bf16 v[46:49], v[86:89], v[198:201], v[46:49]
	v_mfma_f32_16x16x32_bf16 v[42:45], v[94:97], v[198:201], v[42:45]
	v_mfma_f32_16x16x32_bf16 v[30:33], v[86:89], v[216:219], v[30:33]
	v_mfma_f32_16x16x32_bf16 v[26:29], v[94:97], v[216:219], v[26:29]
	v_mfma_f32_16x16x32_bf16 v[10:13], v[86:89], v[224:227], v[10:13]
	v_mfma_f32_16x16x32_bf16 v[6:9], v[94:97], v[224:227], v[6:9]
	s_setprio 0
	s_setprio 1
	v_mfma_f32_16x16x32_bf16 v[54:57], v[98:101], v[186:189], v[54:57]
	v_mfma_f32_16x16x32_bf16 v[50:53], v[106:109], v[186:189], v[50:53]
	v_mfma_f32_16x16x32_bf16 v[38:41], v[98:101], v[194:197], v[38:41]
	v_mfma_f32_16x16x32_bf16 v[34:37], v[106:109], v[194:197], v[34:37]
	v_mfma_f32_16x16x32_bf16 v[22:25], v[98:101], v[202:205], v[22:25]
	v_mfma_f32_16x16x32_bf16 v[18:21], v[106:109], v[202:205], v[18:21]
	v_mfma_f32_16x16x32_bf16 v[14:17], v[98:101], v[220:223], v[14:17]
	v_mfma_f32_16x16x32_bf16 v[2:5], v[106:109], v[220:223], v[2:5]
	v_mfma_f32_16x16x32_bf16 v[54:57], v[102:105], v[190:193], v[54:57]
	v_mfma_f32_16x16x32_bf16 v[50:53], v[110:113], v[190:193], v[50:53]
	v_mfma_f32_16x16x32_bf16 v[38:41], v[102:105], v[198:201], v[38:41]
	v_mfma_f32_16x16x32_bf16 v[34:37], v[110:113], v[198:201], v[34:37]
	v_mfma_f32_16x16x32_bf16 v[22:25], v[102:105], v[216:219], v[22:25]
	v_mfma_f32_16x16x32_bf16 v[18:21], v[110:113], v[216:219], v[18:21]
	v_mfma_f32_16x16x32_bf16 v[14:17], v[102:105], v[224:227], v[14:17]
	v_mfma_f32_16x16x32_bf16 v[2:5], v[110:113], v[224:227], v[2:5]
	s_setprio 0
	s_barrier
; #define PG8_STAGE(bufoff, gbase, voff) do { _Pragma("unroll") for (int _i = 0; _i < 2; ++_i) \
;         __builtin_amdgcn_global_load_lds((const unsigned*)((const char*)(gbase) + (voff)[_i]), (PG8_LAS unsigned*)(lds + (bufoff) + ldsw + _i * 8192), 16, 0, 0); } while (0)
; #define PG8_LDA(dst, b, h) do { _Pragma("unroll") for (int m = 0; m < 4; ++m) _Pragma("unroll") for (int k = 0; k < 2; ++k) dst[m][k] = *(const PG8_LAS bf16x8*)(lds + PG8_SA(b, h) + aoff + m * 2048 + k * 1024); } while (0)
; #define PG8_LDB(dst, b, h) do { _Pragma("unroll") for (int n = 0; n < 2; ++n) _Pragma("unroll") for (int k = 0; k < 2; ++k) dst[n][k] = *(const PG8_LAS bf16x8*)(lds + PG8_SB(b, h) + boff + n * 2048 + k * 1024); } while (0)
; #define PG8_MMA(ai, bj, At, Bt) do { __builtin_amdgcn_s_setprio(1); _Pragma("unroll") for (int m = 0; m < 4; ++m) _Pragma("unroll") for (int n = 0; n < 2; ++n) _Pragma("unroll") for (int k = 0; k < 2; ++k) \
;         acc[ai][bj][m][n] = __builtin_amdgcn_mfma_f32_16x16x32_bf16(Bt[n][k], At[m][k], acc[ai][bj][m][n], 0, 0, 0); __builtin_amdgcn_s_setprio(0); } while (0)
; #define PG8_WAIT_V(n) asm volatile("s_waitcnt vmcnt(" #n ")" ::: "memory")
; #define PG8_WAIT_L(n) asm volatile("s_waitcnt lgkmcnt(" #n ")" ::: "memory")
; #define PG8_BAR __builtin_amdgcn_s_barrier()
; #define PG8_SCHED __builtin_amdgcn_sched_barrier(0)
; template <class Epi, class Sched, bool ALIGN_EPI = false, bool SP2 = false>
; __device__ __forceinline__ void gemm_phase(PG8_LAS unsigned char* lds, const Gemm g, const Sched& S, const Epi& E) {
;     ...
;             PG8_LDB(B0, 1, 0); PG8_LDB(B1, 1, 1); PG8_SCHED; PG8_LDA(At, 1, 0); PG8_STAGE(PG8_SA(0, 1), a2 + hstep, voffA);
;             PG8_WAIT_V(8); PG8_WAIT_L(0); PG8_BAR; PG8_MMA(0, 0, At, B0); PG8_MMA(0, 1, At, B1); PG8_BAR; PG8_SCHED;
;             PG8_LDA(At, 1, 1); PG8_STAGE(PG8_SB(1, 0), b3, voffB); PG8_STAGE(PG8_SB(1, 1), b3 + hstep, voffB); PG8_STAGE(PG8_SA(1, 0), a3, voffA);
;             PG8_WAIT_V(8); PG8_WAIT_L(0); PG8_BAR; PG8_MMA(1, 0, At, B0); PG8_MMA(1, 1, At, B1); PG8_BAR; PG8_SCHED;
;     ...
;         if constexpr (ALIGN_EPI) { if (wr == 0) PG8_BAR; }
	ds_read_b128 v[82:85], v210
	ds_read_b128 v[86:89], v210 offset:1024
	ds_read_b128 v[90:93], v210 offset:2048
	ds_read_b128 v[94:97], v210 offset:3072
	ds_read_b128 v[98:101], v211
	ds_read_b128 v[102:105], v211 offset:1024
	ds_read_b128 v[106:109], v211 offset:2048
	ds_read_b128 v[110:113], v211 offset:3072
	s_add_u32 s72, s72, 0x80000
	s_addc_u32 s73, s73, 0
	s_mov_b32 m0, s58
	ds_read_b128 v[186:189], v209 offset:32768
	ds_read_b128 v[190:193], v209 offset:33792
	ds_read_b128 v[194:197], v209 offset:34816
	ds_read_b128 v[198:201], v209 offset:35840
	ds_read_b128 v[202:205], v209 offset:36864
	ds_read_b128 v[216:219], v209 offset:37888
	ds_read_b128 v[220:223], v209 offset:38912
	ds_read_b128 v[224:227], v209 offset:39936
	global_load_lds_dwordx4 v172, s[72:73]
	s_mov_b32 m0, s59
	s_nop 0
	global_load_lds_dwordx4 v168, s[72:73]
	s_waitcnt vmcnt(8)
	s_waitcnt lgkmcnt(0)
	s_barrier
	s_setprio 1
	s_waitcnt lgkmcnt(0)
	v_mfma_f32_16x16x32_bf16 v[158:161], v[82:85], v[186:189], v[158:161]
	v_mfma_f32_16x16x32_bf16 v[154:157], v[90:93], v[186:189], v[154:157]
	v_mfma_f32_16x16x32_bf16 v[142:145], v[82:85], v[194:197], v[142:145]
	v_mfma_f32_16x16x32_bf16 v[138:141], v[90:93], v[194:197], v[138:141]
	v_mfma_f32_16x16x32_bf16 v[126:129], v[82:85], v[202:205], v[126:129]
	v_mfma_f32_16x16x32_bf16 v[122:125], v[90:93], v[202:205], v[122:125]
	v_mfma_f32_16x16x32_bf16 v[78:81], v[82:85], v[220:223], v[78:81]
	v_mfma_f32_16x16x32_bf16 v[70:73], v[90:93], v[220:223], v[70:73]
	v_mfma_f32_16x16x32_bf16 v[158:161], v[86:89], v[190:193], v[158:161]
	v_mfma_f32_16x16x32_bf16 v[154:157], v[94:97], v[190:193], v[154:157]
	v_mfma_f32_16x16x32_bf16 v[142:145], v[86:89], v[198:201], v[142:145]
	v_mfma_f32_16x16x32_bf16 v[138:141], v[94:97], v[198:201], v[138:141]
	v_mfma_f32_16x16x32_bf16 v[126:129], v[86:89], v[216:219], v[126:129]
	v_mfma_f32_16x16x32_bf16 v[122:125], v[94:97], v[216:219], v[122:125]
	v_mfma_f32_16x16x32_bf16 v[78:81], v[86:89], v[224:227], v[78:81]
	v_mfma_f32_16x16x32_bf16 v[70:73], v[94:97], v[224:227], v[70:73]
	s_setprio 0
	s_setprio 1
	v_mfma_f32_16x16x32_bf16 v[150:153], v[98:101], v[186:189], v[150:153]
	v_mfma_f32_16x16x32_bf16 v[146:149], v[106:109], v[186:189], v[146:149]
	v_mfma_f32_16x16x32_bf16 v[134:137], v[98:101], v[194:197], v[134:137]
	v_mfma_f32_16x16x32_bf16 v[130:133], v[106:109], v[194:197], v[130:133]
	v_mfma_f32_16x16x32_bf16 v[118:121], v[98:101], v[202:205], v[118:121]
	v_mfma_f32_16x16x32_bf16 v[114:117], v[106:109], v[202:205], v[114:117]
	v_mfma_f32_16x16x32_bf16 v[74:77], v[98:101], v[220:223], v[74:77]
	v_mfma_f32_16x16x32_bf16 v[66:69], v[106:109], v[220:223], v[66:69]
	v_mfma_f32_16x16x32_bf16 v[150:153], v[102:105], v[190:193], v[150:153]
	v_mfma_f32_16x16x32_bf16 v[146:149], v[110:113], v[190:193], v[146:149]
	v_mfma_f32_16x16x32_bf16 v[134:137], v[102:105], v[198:201], v[134:137]
	v_mfma_f32_16x16x32_bf16 v[130:133], v[110:113], v[198:201], v[130:133]
	v_mfma_f32_16x16x32_bf16 v[118:121], v[102:105], v[216:219], v[118:121]
	v_mfma_f32_16x16x32_bf16 v[114:117], v[110:113], v[216:219], v[114:117]
	v_mfma_f32_16x16x32_bf16 v[74:77], v[102:105], v[224:227], v[74:77]
	v_mfma_f32_16x16x32_bf16 v[66:69], v[110:113], v[224:227], v[66:69]
	s_setprio 0
	s_barrier
	s_add_i32 s72, s77, s16
	s_nop 0
	s_mov_b32 m0, s72
	ds_read_b128 v[186:189], v209 offset:49152
	ds_read_b128 v[190:193], v209 offset:50176
	ds_read_b128 v[194:197], v209 offset:51200
	ds_read_b128 v[198:201], v209 offset:52224
	ds_read_b128 v[202:205], v209 offset:53248
	ds_read_b128 v[216:219], v209 offset:54272
	ds_read_b128 v[220:223], v209 offset:55296
	ds_read_b128 v[224:227], v209 offset:56320
	global_load_lds_dwordx4 v170, s[98:99]
	s_add_i32 m0, s72, 0x2000
	s_add_u32 s70, s70, 0x80080
	s_nop 0
	s_addc_u32 s71, s71, 0
	s_add_i32 s72, s78, s16
	global_load_lds_dwordx4 v166, s[98:99]
	s_mov_b32 m0, s72
	s_nop 0
	global_load_lds_dwordx4 v170, s[70:71]
	s_add_i32 m0, s72, 0x2000
	s_nop 0
	global_load_lds_dwordx4 v166, s[70:71]
	s_nop 0
	s_mov_b32 m0, s61
	s_nop 0
	global_load_lds_dwordx4 v172, s[100:101]
	s_nop 0
	s_mov_b32 m0, s62
	s_nop 0
	global_load_lds_dwordx4 v168, s[100:101]
	s_waitcnt vmcnt(8)
	s_waitcnt lgkmcnt(0)
	s_barrier
	s_setprio 1
	s_waitcnt lgkmcnt(0)
	v_mfma_f32_16x16x32_bf16 v[62:65], v[82:85], v[186:189], v[62:65]
	v_mfma_f32_16x16x32_bf16 v[58:61], v[90:93], v[186:189], v[58:61]
	v_mfma_f32_16x16x32_bf16 v[46:49], v[82:85], v[194:197], v[46:49]
	v_mfma_f32_16x16x32_bf16 v[42:45], v[90:93], v[194:197], v[42:45]
	v_mfma_f32_16x16x32_bf16 v[30:33], v[82:85], v[202:205], v[30:33]
	v_mfma_f32_16x16x32_bf16 v[26:29], v[90:93], v[202:205], v[26:29]
	v_mfma_f32_16x16x32_bf16 v[10:13], v[82:85], v[220:223], v[10:13]
	v_mfma_f32_16x16x32_bf16 v[6:9], v[90:93], v[220:223], v[6:9]
	v_mfma_f32_16x16x32_bf16 v[62:65], v[86:89], v[190:193], v[62:65]
	v_mfma_f32_16x16x32_bf16 v[58:61], v[94:97], v[190:193], v[58:61]
	v_mfma_f32_16x16x32_bf16 v[46:49], v[86:89], v[198:201], v[46:49]
	v_mfma_f32_16x16x32_bf16 v[42:45], v[94:97], v[198:201], v[42:45]
	v_mfma_f32_16x16x32_bf16 v[30:33], v[86:89], v[216:219], v[30:33]
	v_mfma_f32_16x16x32_bf16 v[26:29], v[94:97], v[216:219], v[26:29]
	v_mfma_f32_16x16x32_bf16 v[10:13], v[86:89], v[224:227], v[10:13]
	v_mfma_f32_16x16x32_bf16 v[6:9], v[94:97], v[224:227], v[6:9]
	s_setprio 0
	s_setprio 1
	v_mfma_f32_16x16x32_bf16 v[54:57], v[98:101], v[186:189], v[54:57]
	v_mfma_f32_16x16x32_bf16 v[50:53], v[106:109], v[186:189], v[50:53]
	v_mfma_f32_16x16x32_bf16 v[38:41], v[98:101], v[194:197], v[38:41]
	v_mfma_f32_16x16x32_bf16 v[34:37], v[106:109], v[194:197], v[34:37]
	v_mfma_f32_16x16x32_bf16 v[22:25], v[98:101], v[202:205], v[22:25]
	v_mfma_f32_16x16x32_bf16 v[18:21], v[106:109], v[202:205], v[18:21]
	v_mfma_f32_16x16x32_bf16 v[14:17], v[98:101], v[220:223], v[14:17]
	v_mfma_f32_16x16x32_bf16 v[2:5], v[106:109], v[220:223], v[2:5]
	v_mfma_f32_16x16x32_bf16 v[54:57], v[102:105], v[190:193], v[54:57]
	v_mfma_f32_16x16x32_bf16 v[50:53], v[110:113], v[190:193], v[50:53]
	v_mfma_f32_16x16x32_bf16 v[38:41], v[102:105], v[198:201], v[38:41]
	v_mfma_f32_16x16x32_bf16 v[34:37], v[110:113], v[198:201], v[34:37]
	v_mfma_f32_16x16x32_bf16 v[22:25], v[102:105], v[216:219], v[22:25]
	v_mfma_f32_16x16x32_bf16 v[18:21], v[110:113], v[216:219], v[18:21]
	v_mfma_f32_16x16x32_bf16 v[14:17], v[102:105], v[224:227], v[14:17]
	v_mfma_f32_16x16x32_bf16 v[2:5], v[110:113], v[224:227], v[2:5]
	s_setprio 0
	s_barrier
	s_add_i32 s86, s86, 2
	s_add_u32 s68, s68, 0x100
	s_addc_u32 s69, s69, 0
	s_add_u32 s84, s84, 0x100
	s_addc_u32 s85, s85, 0
	s_cmp_gt_u32 s86, 29
	s_cbranch_scc0 .LBB0_908
	s_and_b64 vcc, exec, s[38:39]
	s_cbranch_vccz .LBB0_911
	s_barrier

; #define PG8_STAGE(bufoff, gbase, voff) do { _Pragma("unroll") for (int _i = 0; _i < 2; ++_i) \
;         __builtin_amdgcn_global_load_lds((const unsigned*)((const char*)(gbase) + (voff)[_i]), (PG8_LAS unsigned*)(lds + (bufoff) + ldsw + _i * 8192), 16, 0, 0); } while (0)
; #define PG8_LDA(dst, b, h) do { _Pragma("unroll") for (int m = 0; m < 4; ++m) _Pragma("unroll") for (int k = 0; k < 2; ++k) dst[m][k] = *(const PG8_LAS bf16x8*)(lds + PG8_SA(b, h) + aoff + m * 2048 + k * 1024); } while (0)
; #define PG8_LDB(dst, b, h) do { _Pragma("unroll") for (int n = 0; n < 2; ++n) _Pragma("unroll") for (int k = 0; k < 2; ++k) dst[n][k] = *(const PG8_LAS bf16x8*)(lds + PG8_SB(b, h) + boff + n * 2048 + k * 1024); } while (0)
; #define PG8_MMA(ai, bj, At, Bt) do { __builtin_amdgcn_s_setprio(1); _Pragma("unroll") for (int m = 0; m < 4; ++m) _Pragma("unroll") for (int n = 0; n < 2; ++n) _Pragma("unroll") for (int k = 0; k < 2; ++k) \
;         acc[ai][bj][m][n] = __builtin_amdgcn_mfma_f32_16x16x32_bf16(Bt[n][k], At[m][k], acc[ai][bj][m][n], 0, 0, 0); __builtin_amdgcn_s_setprio(0); } while (0)
; #define PG8_WAIT_V(n) asm volatile("s_waitcnt vmcnt(" #n ")" ::: "memory")
; #define PG8_BAR __builtin_amdgcn_s_barrier()
; template <class Epi, class Sched, bool ALIGN_EPI = false, bool SP2 = false>
; __device__ __forceinline__ void gemm_phase(PG8_LAS unsigned char* lds, const Gemm g, const Sched& S, const Epi& E) {
;     ...
;         for (int t = 0; t < nt; t += 2) {
;             const bool last = (t == nt - 2);
;             const char* a1 = cA + (size_t)(t + 1) * kstep;
;             const char* a2 = last ? nA : cA + (size_t)(t + 2) * kstep; const char* b2 = last ? nB : cB + (size_t)(t + 2) * kstep;
;             const char* a3 = a2 + kstep; const char* b3 = b2 + kstep;
;             if (last && has_next) S.a_ready(nxt);
;             if constexpr (SP2) {
;             PG8_LDB(B0, 0, 0); PG8_LDB(B1, 0, 1); PG8_SCHED; PG8_LDA(At, 0, 0); PG8_STAGE(PG8_SA(1, 1), a1 + hstep, voffA);
;             PG8_WAIT_V(8); PG8_WAIT_L(0); PG8_BAR; PG8_MMA(0, 0, At, B0); PG8_MMA(0, 1, At, B1); PG8_BAR; PG8_SCHED;
;             PG8_LDA(At, 0, 1); PG8_STAGE(PG8_SB(0, 0), b2, voffB); PG8_STAGE(PG8_SB(0, 1), b2 + hstep, voffB); PG8_STAGE(PG8_SA(0, 0), a2, voffA);
;             PG8_WAIT_V(8); PG8_WAIT_L(0); PG8_BAR; PG8_MMA(1, 0, At, B0); PG8_MMA(1, 1, At, B1); PG8_BAR; PG8_SCHED;
.LBB0_994:
	ds_read_b128 v[146:149], v152
	ds_read_b128 v[158:161], v152 offset:1024
	ds_read_b128 v[166:169], v152 offset:2048
	ds_read_b128 v[170:173], v152 offset:3072
	ds_read_b128 v[174:177], v153
	ds_read_b128 v[178:181], v153 offset:1024
	ds_read_b128 v[182:185], v153 offset:2048
	ds_read_b128 v[186:189], v153 offset:3072
	s_add_u32 s38, s36, 0xffea0080
	s_addc_u32 s39, s37, -1
	s_cmpk_eq_i32 s63, 0x54
	s_cselect_b32 s41, s5, s39
	s_cselect_b32 s40, s4, s38
	s_cselect_b32 s39, s29, s62
	s_cselect_b32 s38, s28, s61
	s_add_i32 m0, s16, 0xc000
	ds_read_b128 v[190:193], v154
	ds_read_b128 v[194:197], v154 offset:1024
	ds_read_b128 v[198:201], v154 offset:2048
	ds_read_b128 v[202:205], v154 offset:3072
	ds_read_b128 v[208:211], v154 offset:4096
	ds_read_b128 v[212:215], v154 offset:5120
	ds_read_b128 v[216:219], v154 offset:6144
	ds_read_b128 v[220:223], v154 offset:7168
	global_load_lds_dwordx4 v138, s[36:37]
	s_add_i32 m0, s16, 0xe000
	s_nop 0
	global_load_lds_dwordx4 v140, s[36:37]
	s_waitcnt vmcnt(8)
	s_waitcnt lgkmcnt(0)
	s_barrier
	s_setprio 1
	s_waitcnt lgkmcnt(0)
	v_mfma_f32_16x16x32_bf16 v[126:129], v[146:149], v[190:193], v[126:129]
	v_mfma_f32_16x16x32_bf16 v[122:125], v[166:169], v[190:193], v[122:125]
	v_mfma_f32_16x16x32_bf16 v[110:113], v[146:149], v[198:201], v[110:113]
	v_mfma_f32_16x16x32_bf16 v[106:109], v[166:169], v[198:201], v[106:109]
	v_mfma_f32_16x16x32_bf16 v[94:97], v[146:149], v[208:211], v[94:97]
	v_mfma_f32_16x16x32_bf16 v[90:93], v[166:169], v[208:211], v[90:93]
	v_mfma_f32_16x16x32_bf16 v[78:81], v[146:149], v[216:219], v[78:81]
	v_mfma_f32_16x16x32_bf16 v[74:77], v[166:169], v[216:219], v[74:77]
	v_mfma_f32_16x16x32_bf16 v[126:129], v[158:161], v[194:197], v[126:129]
	v_mfma_f32_16x16x32_bf16 v[122:125], v[170:173], v[194:197], v[122:125]
	v_mfma_f32_16x16x32_bf16 v[110:113], v[158:161], v[202:205], v[110:113]
	v_mfma_f32_16x16x32_bf16 v[106:109], v[170:173], v[202:205], v[106:109]
	v_mfma_f32_16x16x32_bf16 v[94:97], v[158:161], v[212:215], v[94:97]
	v_mfma_f32_16x16x32_bf16 v[90:93], v[170:173], v[212:215], v[90:93]
	v_mfma_f32_16x16x32_bf16 v[78:81], v[158:161], v[220:223], v[78:81]
	v_mfma_f32_16x16x32_bf16 v[74:77], v[170:173], v[220:223], v[74:77]
	s_setprio 0
	s_setprio 1
	v_mfma_f32_16x16x32_bf16 v[118:121], v[174:177], v[190:193], v[118:121]
	v_mfma_f32_16x16x32_bf16 v[114:117], v[182:185], v[190:193], v[114:117]
	v_mfma_f32_16x16x32_bf16 v[102:105], v[174:177], v[198:201], v[102:105]
	v_mfma_f32_16x16x32_bf16 v[98:101], v[182:185], v[198:201], v[98:101]
	v_mfma_f32_16x16x32_bf16 v[86:89], v[174:177], v[208:211], v[86:89]
	v_mfma_f32_16x16x32_bf16 v[82:85], v[182:185], v[208:211], v[82:85]
	v_mfma_f32_16x16x32_bf16 v[70:73], v[174:177], v[216:219], v[70:73]
	v_mfma_f32_16x16x32_bf16 v[66:69], v[182:185], v[216:219], v[66:69]
	v_mfma_f32_16x16x32_bf16 v[118:121], v[178:181], v[194:197], v[118:121]
	v_mfma_f32_16x16x32_bf16 v[114:117], v[186:189], v[194:197], v[114:117]
	v_mfma_f32_16x16x32_bf16 v[102:105], v[178:181], v[202:205], v[102:105]
	v_mfma_f32_16x16x32_bf16 v[98:101], v[186:189], v[202:205], v[98:101]
	v_mfma_f32_16x16x32_bf16 v[86:89], v[178:181], v[212:215], v[86:89]
	v_mfma_f32_16x16x32_bf16 v[82:85], v[186:189], v[212:215], v[82:85]
	v_mfma_f32_16x16x32_bf16 v[70:73], v[178:181], v[220:223], v[70:73]
	v_mfma_f32_16x16x32_bf16 v[66:69], v[186:189], v[220:223], v[66:69]
	s_setprio 0
	s_barrier
	s_add_u32 s98, s38, s14
	s_addc_u32 s99, s39, s15
	s_add_u32 s100, s40, s14
	s_addc_u32 s101, s41, s15
	s_add_i32 s64, s47, s2
	s_nop 0
	s_mov_b32 m0, s64
	ds_read_b128 v[190:193], v154 offset:16384
	ds_read_b128 v[194:197], v154 offset:17408
	ds_read_b128 v[198:201], v154 offset:18432
	ds_read_b128 v[202:205], v154 offset:19456
	ds_read_b128 v[208:211], v154 offset:20480
	ds_read_b128 v[212:215], v154 offset:21504
	ds_read_b128 v[216:219], v154 offset:22528
	ds_read_b128 v[220:223], v154 offset:23552
	global_load_lds_dwordx4 v132, s[38:39]
	s_add_i32 m0, s64, 0x2000
	s_add_u32 s64, s38, 0x160000
	s_nop 0
	s_addc_u32 s65, s39, 0
	s_add_i32 s66, s48, s2
	global_load_lds_dwordx4 v136, s[38:39]
	s_mov_b32 m0, s66
	s_nop 0
	global_load_lds_dwordx4 v132, s[64:65]
	s_add_i32 m0, s66, 0x2000
	s_nop 0
	global_load_lds_dwordx4 v136, s[64:65]
	s_nop 0
	s_mov_b32 m0, s16
	s_nop 0
	global_load_lds_dwordx4 v130, s[40:41]
	s_mov_b32 m0, s17
	s_nop 0
	global_load_lds_dwordx4 v134, s[40:41]
	s_waitcnt vmcnt(8)
	s_waitcnt lgkmcnt(0)
	s_barrier
	s_setprio 1
	s_waitcnt lgkmcnt(0)
	v_mfma_f32_16x16x32_bf16 v[62:65], v[146:149], v[190:193], v[62:65]
	v_mfma_f32_16x16x32_bf16 v[58:61], v[166:169], v[190:193], v[58:61]
	v_mfma_f32_16x16x32_bf16 v[46:49], v[146:149], v[198:201], v[46:49]
	v_mfma_f32_16x16x32_bf16 v[42:45], v[166:169], v[198:201], v[42:45]
	v_mfma_f32_16x16x32_bf16 v[30:33], v[146:149], v[208:211], v[30:33]
	v_mfma_f32_16x16x32_bf16 v[26:29], v[166:169], v[208:211], v[26:29]
	v_mfma_f32_16x16x32_bf16 v[14:17], v[146:149], v[216:219], v[14:17]
	v_mfma_f32_16x16x32_bf16 v[10:13], v[166:169], v[216:219], v[10:13]
	v_mfma_f32_16x16x32_bf16 v[62:65], v[158:161], v[194:197], v[62:65]
	v_mfma_f32_16x16x32_bf16 v[58:61], v[170:173], v[194:197], v[58:61]
	v_mfma_f32_16x16x32_bf16 v[46:49], v[158:161], v[202:205], v[46:49]
	v_mfma_f32_16x16x32_bf16 v[42:45], v[170:173], v[202:205], v[42:45]
	v_mfma_f32_16x16x32_bf16 v[30:33], v[158:161], v[212:215], v[30:33]
	v_mfma_f32_16x16x32_bf16 v[26:29], v[170:173], v[212:215], v[26:29]
	v_mfma_f32_16x16x32_bf16 v[14:17], v[158:161], v[220:223], v[14:17]
	v_mfma_f32_16x16x32_bf16 v[10:13], v[170:173], v[220:223], v[10:13]
	s_setprio 0
	s_setprio 1
	v_mfma_f32_16x16x32_bf16 v[54:57], v[174:177], v[190:193], v[54:57]
	v_mfma_f32_16x16x32_bf16 v[50:53], v[182:185], v[190:193], v[50:53]
	v_mfma_f32_16x16x32_bf16 v[38:41], v[174:177], v[198:201], v[38:41]
	v_mfma_f32_16x16x32_bf16 v[34:37], v[182:185], v[198:201], v[34:37]
	v_mfma_f32_16x16x32_bf16 v[22:25], v[174:177], v[208:211], v[22:25]
	v_mfma_f32_16x16x32_bf16 v[18:21], v[182:185], v[208:211], v[18:21]
	v_mfma_f32_16x16x32_bf16 v[6:9], v[174:177], v[216:219], v[6:9]
	v_mfma_f32_16x16x32_bf16 v[2:5], v[182:185], v[216:219], v[2:5]
	v_mfma_f32_16x16x32_bf16 v[54:57], v[178:181], v[194:197], v[54:57]
	v_mfma_f32_16x16x32_bf16 v[50:53], v[186:189], v[194:197], v[50:53]
	v_mfma_f32_16x16x32_bf16 v[38:41], v[178:181], v[202:205], v[38:41]
	v_mfma_f32_16x16x32_bf16 v[34:37], v[186:189], v[202:205], v[34:37]
	v_mfma_f32_16x16x32_bf16 v[22:25], v[178:181], v[212:215], v[22:25]
	v_mfma_f32_16x16x32_bf16 v[18:21], v[186:189], v[212:215], v[18:21]
	v_mfma_f32_16x16x32_bf16 v[6:9], v[178:181], v[220:223], v[6:9]
	v_mfma_f32_16x16x32_bf16 v[2:5], v[186:189], v[220:223], v[2:5]
	s_setprio 0
	s_barrier
; #define PG8_STAGE(bufoff, gbase, voff) do { _Pragma("unroll") for (int _i = 0; _i < 2; ++_i) \
;         __builtin_amdgcn_global_load_lds((const unsigned*)((const char*)(gbase) + (voff)[_i]), (PG8_LAS unsigned*)(lds + (bufoff) + ldsw + _i * 8192), 16, 0, 0); } while (0)
; #define PG8_LDA(dst, b, h) do { _Pragma("unroll") for (int m = 0; m < 4; ++m) _Pragma("unroll") for (int k = 0; k < 2; ++k) dst[m][k] = *(const PG8_LAS bf16x8*)(lds + PG8_SA(b, h) + aoff + m * 2048 + k * 1024); } while (0)
; #define PG8_LDB(dst, b, h) do { _Pragma("unroll") for (int n = 0; n < 2; ++n) _Pragma("unroll") for (int k = 0; k < 2; ++k) dst[n][k] = *(const PG8_LAS bf16x8*)(lds + PG8_SB(b, h) + boff + n * 2048 + k * 1024); } while (0)
; #define PG8_MMA(ai, bj, At, Bt) do { __builtin_amdgcn_s_setprio(1); _Pragma("unroll") for (int m = 0; m < 4; ++m) _Pragma("unroll") for (int n = 0; n < 2; ++n) _Pragma("unroll") for (int k = 0; k < 2; ++k) \
;         acc[ai][bj][m][n] = __builtin_amdgcn_mfma_f32_16x16x32_bf16(Bt[n][k], At[m][k], acc[ai][bj][m][n], 0, 0, 0); __builtin_amdgcn_s_setprio(0); } while (0)
; #define PG8_WAIT_V(n) asm volatile("s_waitcnt vmcnt(" #n ")" ::: "memory")
; #define PG8_WAIT_L(n) asm volatile("s_waitcnt lgkmcnt(" #n ")" ::: "memory")
; #define PG8_BAR __builtin_amdgcn_s_barrier()
; #define PG8_SCHED __builtin_amdgcn_sched_barrier(0)
; template <class Epi, class Sched, bool ALIGN_EPI = false, bool SP2 = false>
; __device__ __forceinline__ void gemm_phase(PG8_LAS unsigned char* lds, const Gemm g, const Sched& S, const Epi& E) {
;     ...
;             PG8_LDB(B0, 1, 0); PG8_LDB(B1, 1, 1); PG8_SCHED; PG8_LDA(At, 1, 0); PG8_STAGE(PG8_SA(0, 1), a2 + hstep, voffA);
;             PG8_WAIT_V(8); PG8_WAIT_L(0); PG8_BAR; PG8_MMA(0, 0, At, B0); PG8_MMA(0, 1, At, B1); PG8_BAR; PG8_SCHED;
;             PG8_LDA(At, 1, 1); PG8_STAGE(PG8_SB(1, 0), b3, voffB); PG8_STAGE(PG8_SB(1, 1), b3 + hstep, voffB); PG8_STAGE(PG8_SA(1, 0), a3, voffA);
;             PG8_WAIT_V(8); PG8_WAIT_L(0); PG8_BAR; PG8_MMA(1, 0, At, B0); PG8_MMA(1, 1, At, B1); PG8_BAR; PG8_SCHED;
;     ...
;         if constexpr (ALIGN_EPI) { if (wr == 0) PG8_BAR; }
	ds_read_b128 v[146:149], v155
	ds_read_b128 v[158:161], v155 offset:1024
	ds_read_b128 v[166:169], v155 offset:2048
	ds_read_b128 v[170:173], v155 offset:3072
	ds_read_b128 v[174:177], v156
	ds_read_b128 v[178:181], v156 offset:1024
	ds_read_b128 v[182:185], v156 offset:2048
	ds_read_b128 v[186:189], v156 offset:3072
	s_add_u32 s40, s40, 0x160000
	s_addc_u32 s41, s41, 0
	s_mov_b32 m0, s33
	ds_read_b128 v[190:193], v154 offset:32768
	ds_read_b128 v[194:197], v154 offset:33792
	ds_read_b128 v[198:201], v154 offset:34816
	ds_read_b128 v[202:205], v154 offset:35840
	ds_read_b128 v[208:211], v154 offset:36864
	ds_read_b128 v[212:215], v154 offset:37888
	ds_read_b128 v[216:219], v154 offset:38912
	ds_read_b128 v[220:223], v154 offset:39936
	global_load_lds_dwordx4 v130, s[40:41]
	s_mov_b32 m0, s35
	s_nop 0
	global_load_lds_dwordx4 v134, s[40:41]
	s_waitcnt vmcnt(8)
	s_waitcnt lgkmcnt(0)
	s_barrier
	s_setprio 1
	s_waitcnt lgkmcnt(0)
	v_mfma_f32_16x16x32_bf16 v[126:129], v[146:149], v[190:193], v[126:129]
	v_mfma_f32_16x16x32_bf16 v[122:125], v[166:169], v[190:193], v[122:125]
	v_mfma_f32_16x16x32_bf16 v[110:113], v[146:149], v[198:201], v[110:113]
	v_mfma_f32_16x16x32_bf16 v[106:109], v[166:169], v[198:201], v[106:109]
	v_mfma_f32_16x16x32_bf16 v[94:97], v[146:149], v[208:211], v[94:97]
	v_mfma_f32_16x16x32_bf16 v[90:93], v[166:169], v[208:211], v[90:93]
	v_mfma_f32_16x16x32_bf16 v[78:81], v[146:149], v[216:219], v[78:81]
	v_mfma_f32_16x16x32_bf16 v[74:77], v[166:169], v[216:219], v[74:77]
	v_mfma_f32_16x16x32_bf16 v[126:129], v[158:161], v[194:197], v[126:129]
	v_mfma_f32_16x16x32_bf16 v[122:125], v[170:173], v[194:197], v[122:125]
	v_mfma_f32_16x16x32_bf16 v[110:113], v[158:161], v[202:205], v[110:113]
	v_mfma_f32_16x16x32_bf16 v[106:109], v[170:173], v[202:205], v[106:109]
	v_mfma_f32_16x16x32_bf16 v[94:97], v[158:161], v[212:215], v[94:97]
	v_mfma_f32_16x16x32_bf16 v[90:93], v[170:173], v[212:215], v[90:93]
	v_mfma_f32_16x16x32_bf16 v[78:81], v[158:161], v[220:223], v[78:81]
	v_mfma_f32_16x16x32_bf16 v[74:77], v[170:173], v[220:223], v[74:77]
	s_setprio 0
	s_setprio 1
	v_mfma_f32_16x16x32_bf16 v[118:121], v[174:177], v[190:193], v[118:121]
	v_mfma_f32_16x16x32_bf16 v[114:117], v[182:185], v[190:193], v[114:117]
	v_mfma_f32_16x16x32_bf16 v[102:105], v[174:177], v[198:201], v[102:105]
	v_mfma_f32_16x16x32_bf16 v[98:101], v[182:185], v[198:201], v[98:101]
	v_mfma_f32_16x16x32_bf16 v[86:89], v[174:177], v[208:211], v[86:89]
	v_mfma_f32_16x16x32_bf16 v[82:85], v[182:185], v[208:211], v[82:85]
	v_mfma_f32_16x16x32_bf16 v[70:73], v[174:177], v[216:219], v[70:73]
	v_mfma_f32_16x16x32_bf16 v[66:69], v[182:185], v[216:219], v[66:69]
	v_mfma_f32_16x16x32_bf16 v[118:121], v[178:181], v[194:197], v[118:121]
	v_mfma_f32_16x16x32_bf16 v[114:117], v[186:189], v[194:197], v[114:117]
	v_mfma_f32_16x16x32_bf16 v[102:105], v[178:181], v[202:205], v[102:105]
	v_mfma_f32_16x16x32_bf16 v[98:101], v[186:189], v[202:205], v[98:101]
	v_mfma_f32_16x16x32_bf16 v[86:89], v[178:181], v[212:215], v[86:89]
	v_mfma_f32_16x16x32_bf16 v[82:85], v[186:189], v[212:215], v[82:85]
	v_mfma_f32_16x16x32_bf16 v[70:73], v[178:181], v[220:223], v[70:73]
	v_mfma_f32_16x16x32_bf16 v[66:69], v[186:189], v[220:223], v[66:69]
	s_setprio 0
	s_barrier
	s_add_i32 s40, s49, s2
	s_nop 0
	s_mov_b32 m0, s40
	ds_read_b128 v[190:193], v154 offset:49152
	ds_read_b128 v[194:197], v154 offset:50176
	ds_read_b128 v[198:201], v154 offset:51200
	ds_read_b128 v[202:205], v154 offset:52224
	ds_read_b128 v[208:211], v154 offset:53248
	ds_read_b128 v[212:215], v154 offset:54272
	ds_read_b128 v[216:219], v154 offset:55296
	ds_read_b128 v[220:223], v154 offset:56320
	global_load_lds_dwordx4 v132, s[98:99]
	s_add_i32 m0, s40, 0x2000
	s_add_u32 s38, s38, 0x160080
	s_nop 0
	s_addc_u32 s39, s39, 0
	s_add_i32 s40, s50, s2
	global_load_lds_dwordx4 v136, s[98:99]
	s_mov_b32 m0, s40
	s_nop 0
	global_load_lds_dwordx4 v132, s[38:39]
	s_add_i32 m0, s40, 0x2000
	s_nop 0
	global_load_lds_dwordx4 v136, s[38:39]
	s_nop 0
	s_mov_b32 m0, s42
	s_nop 0
	global_load_lds_dwordx4 v130, s[100:101]
	s_nop 0
	s_mov_b32 m0, s43
	s_nop 0
	global_load_lds_dwordx4 v134, s[100:101]
	s_waitcnt vmcnt(8)
	s_waitcnt lgkmcnt(0)
	s_barrier
	s_setprio 1
	s_waitcnt lgkmcnt(0)
	v_mfma_f32_16x16x32_bf16 v[62:65], v[146:149], v[190:193], v[62:65]
	v_mfma_f32_16x16x32_bf16 v[58:61], v[166:169], v[190:193], v[58:61]
	v_mfma_f32_16x16x32_bf16 v[46:49], v[146:149], v[198:201], v[46:49]
	v_mfma_f32_16x16x32_bf16 v[42:45], v[166:169], v[198:201], v[42:45]
	v_mfma_f32_16x16x32_bf16 v[30:33], v[146:149], v[208:211], v[30:33]
	v_mfma_f32_16x16x32_bf16 v[26:29], v[166:169], v[208:211], v[26:29]
	v_mfma_f32_16x16x32_bf16 v[14:17], v[146:149], v[216:219], v[14:17]
	v_mfma_f32_16x16x32_bf16 v[10:13], v[166:169], v[216:219], v[10:13]
	v_mfma_f32_16x16x32_bf16 v[62:65], v[158:161], v[194:197], v[62:65]
	v_mfma_f32_16x16x32_bf16 v[58:61], v[170:173], v[194:197], v[58:61]
	v_mfma_f32_16x16x32_bf16 v[46:49], v[158:161], v[202:205], v[46:49]
	v_mfma_f32_16x16x32_bf16 v[42:45], v[170:173], v[202:205], v[42:45]
	v_mfma_f32_16x16x32_bf16 v[30:33], v[158:161], v[212:215], v[30:33]
	v_mfma_f32_16x16x32_bf16 v[26:29], v[170:173], v[212:215], v[26:29]
	v_mfma_f32_16x16x32_bf16 v[14:17], v[158:161], v[220:223], v[14:17]
	v_mfma_f32_16x16x32_bf16 v[10:13], v[170:173], v[220:223], v[10:13]
	s_setprio 0
	s_setprio 1
	v_mfma_f32_16x16x32_bf16 v[54:57], v[174:177], v[190:193], v[54:57]
	v_mfma_f32_16x16x32_bf16 v[50:53], v[182:185], v[190:193], v[50:53]
	v_mfma_f32_16x16x32_bf16 v[38:41], v[174:177], v[198:201], v[38:41]
	v_mfma_f32_16x16x32_bf16 v[34:37], v[182:185], v[198:201], v[34:37]
	v_mfma_f32_16x16x32_bf16 v[22:25], v[174:177], v[208:211], v[22:25]
	v_mfma_f32_16x16x32_bf16 v[18:21], v[182:185], v[208:211], v[18:21]
	v_mfma_f32_16x16x32_bf16 v[6:9], v[174:177], v[216:219], v[6:9]
	v_mfma_f32_16x16x32_bf16 v[2:5], v[182:185], v[216:219], v[2:5]
	v_mfma_f32_16x16x32_bf16 v[54:57], v[178:181], v[194:197], v[54:57]
	v_mfma_f32_16x16x32_bf16 v[50:53], v[186:189], v[194:197], v[50:53]
	v_mfma_f32_16x16x32_bf16 v[38:41], v[178:181], v[202:205], v[38:41]
	v_mfma_f32_16x16x32_bf16 v[34:37], v[186:189], v[202:205], v[34:37]
	v_mfma_f32_16x16x32_bf16 v[22:25], v[178:181], v[212:215], v[22:25]
	v_mfma_f32_16x16x32_bf16 v[18:21], v[186:189], v[212:215], v[18:21]
	v_mfma_f32_16x16x32_bf16 v[6:9], v[178:181], v[220:223], v[6:9]
	v_mfma_f32_16x16x32_bf16 v[2:5], v[186:189], v[220:223], v[2:5]
	s_setprio 0
	s_barrier
	s_add_i32 s63, s63, 2
	s_add_u32 s36, s36, 0x100
	s_addc_u32 s37, s37, 0
	s_add_u32 s61, s61, 0x100
	s_addc_u32 s62, s62, 0
	s_cmpk_gt_u32 s63, 0x55
	s_cbranch_scc0 .LBB0_994
	s_and_b64 vcc, exec, s[26:27]
	s_cbranch_vccz .LBB0_997
	s_barrier
